# strategy 7.4: one static s_setprio 1 for waves 4-7 over each GEMM phase, hipcc's per-MFMA-group priority flips in the six K-loops deleted
# speedup vs baseline: 1.0072x; 1.0072x over previous
; #define PG8_LAS __attribute__((address_space(3)))
; template <class Epi, class Sched, bool ALIGN_EPI = false, bool SP2 = false>
; __device__ __forceinline__ void gemm_phase(PG8_LAS unsigned char* lds, const Gemm g, const Sched& S, const Epi& E, const int tid) {
;     const int wid = __builtin_amdgcn_readfirstlane(tid >> 6), lane = tid & 63, wr = wid >> 2, wc = wid & 3, fr = lane & 15, fq = lane >> 4;
.LBB0_75:
	v_readfirstlane_b32 s98, v158
	s_nop 3
	s_lshr_b32 s98, s98, 6
	s_cmp_ge_u32 s98, 4
	s_cbranch_scc0 .Lprio_skip_0
	s_setprio 1

; #define PG8_STAGE(bufoff, gbase, voff) do { _Pragma("unroll") for (int _i = 0; _i < 2; ++_i) \
;         __builtin_amdgcn_global_load_lds((const unsigned*)((const char*)(gbase) + (voff)[_i]), (PG8_LAS unsigned*)(lds + (bufoff) + ldsw + _i * 8192), 16, 0, 0); } while (0)
; #define PG8_LDA(dst, b, h) do { _Pragma("unroll") for (int m = 0; m < 4; ++m) _Pragma("unroll") for (int k = 0; k < 2; ++k) dst[m][k] = *(const PG8_LAS bf16x8*)(lds + PG8_SA(b, h) + aoff + m * 2048 + k * 1024); } while (0)
; #define PG8_LDB(dst, b, h) do { _Pragma("unroll") for (int n = 0; n < 2; ++n) _Pragma("unroll") for (int k = 0; k < 2; ++k) dst[n][k] = *(const PG8_LAS bf16x8*)(lds + PG8_SB(b, h) + boff + n * 2048 + k * 1024); } while (0)
; #define PG8_MMA(ai, bj, At, Bt) do { __builtin_amdgcn_s_setprio(1); _Pragma("unroll") for (int m = 0; m < 4; ++m) _Pragma("unroll") for (int n = 0; n < 2; ++n) _Pragma("unroll") for (int k = 0; k < 2; ++k) \
;         acc[ai][bj][m][n] = __builtin_amdgcn_mfma_f32_16x16x32_bf16(Bt[n][k], At[m][k], acc[ai][bj][m][n], 0, 0, 0); __builtin_amdgcn_s_setprio(0); } while (0)
; #define PG8_WAIT_V(n) asm volatile("s_waitcnt vmcnt(" #n ")" ::: "memory")
; #define PG8_WAIT_L(n) asm volatile("s_waitcnt lgkmcnt(" #n ")" ::: "memory")
; #define PG8_BAR __builtin_amdgcn_s_barrier()
; #define PG8_SCHED __builtin_amdgcn_sched_barrier(0)
; template <class Epi, class Sched, bool ALIGN_EPI = false, bool SP2 = false>
; __device__ __forceinline__ void gemm_phase(PG8_LAS unsigned char* lds, const Gemm g, const Sched& S, const Epi& E, const int tid) {
;     ...
;             PG8_LDB(B0, 0, 0); PG8_LDB(B1, 0, 1); PG8_SCHED; PG8_LDA(At, 0, 0); PG8_STAGE(PG8_SA(1, 1), a1 + hstep, voffA);
;             PG8_WAIT_V(8); PG8_WAIT_L(0); PG8_BAR; PG8_MMA(0, 0, At, B0); PG8_MMA(0, 1, At, B1); PG8_BAR; PG8_SCHED;
;             PG8_LDA(At, 0, 1); PG8_STAGE(PG8_SB(0, 0), b2, voffB); PG8_STAGE(PG8_SB(0, 1), b2 + hstep, voffB); PG8_STAGE(PG8_SA(0, 0), a2, voffA);
;             PG8_WAIT_V(8); PG8_WAIT_L(0); PG8_BAR; PG8_MMA(1, 0, At, B0); PG8_MMA(1, 1, At, B1); PG8_BAR; PG8_SCHED;
.LBB0_94:
	s_add_u32 s35, s52, 0xfffc0080
	s_addc_u32 s43, s53, -1
	s_add_i32 s45, 0, 0x10000
	s_cmp_eq_u32 s34, 12
	s_cselect_b32 s57, s0, s43
	s_cselect_b32 s56, s1, s35
	s_waitcnt lgkmcnt(0)
	v_add_u32_e32 v156, s45, v5
	s_cselect_b32 s55, s9, s33
	s_cselect_b32 s54, s18, s19
	s_add_i32 s35, 0, 0x14000
	ds_read_b128 v[134:137], v156
	ds_read_b128 v[138:141], v156 offset:1024
	ds_read_b128 v[152:155], v156 offset:2048
	ds_read_b128 v[164:167], v156 offset:3072
	v_add_u32_e32 v156, s35, v5
	ds_read_b128 v[168:171], v156
	ds_read_b128 v[172:175], v156 offset:1024
	ds_read_b128 v[194:197], v156 offset:2048
	ds_read_b128 v[198:201], v156 offset:3072
	v_lshl_add_u64 v[156:157], s[52:53], 0, v[148:149]
	s_add_i32 m0, s61, 0xc000
	ds_read_b128 v[202:205], v191
	ds_read_b128 v[206:209], v191 offset:1024
	ds_read_b128 v[210:213], v191 offset:2048
	ds_read_b128 v[218:221], v191 offset:3072
	ds_read_b128 v[222:225], v191 offset:4096
	ds_read_b128 v[226:229], v191 offset:5120
	ds_read_b128 v[230:233], v191 offset:6144
	ds_read_b128 v[234:237], v191 offset:7168
	global_load_lds_dwordx4 v[156:157], off
	v_lshl_add_u64 v[156:157], s[52:53], 0, v[150:151]
	s_add_i32 m0, s61, 0xe000
	s_nop 0
	global_load_lds_dwordx4 v[156:157], off
	s_waitcnt vmcnt(8)
	s_waitcnt lgkmcnt(0)
	s_barrier
	s_waitcnt lgkmcnt(0)
	v_mfma_f32_16x16x32_bf16 v[130:133], v[134:137], v[202:205], v[130:133]
	v_mfma_f32_16x16x32_bf16 v[126:129], v[152:155], v[202:205], v[126:129]
	v_mfma_f32_16x16x32_bf16 v[114:117], v[134:137], v[210:213], v[114:117]
	v_mfma_f32_16x16x32_bf16 v[110:113], v[152:155], v[210:213], v[110:113]
	v_mfma_f32_16x16x32_bf16 v[98:101], v[134:137], v[222:225], v[98:101]
	v_mfma_f32_16x16x32_bf16 v[94:97], v[152:155], v[222:225], v[94:97]
	v_mfma_f32_16x16x32_bf16 v[82:85], v[134:137], v[230:233], v[82:85]
	v_mfma_f32_16x16x32_bf16 v[78:81], v[152:155], v[230:233], v[78:81]
	v_mfma_f32_16x16x32_bf16 v[130:133], v[138:141], v[206:209], v[130:133]
	v_mfma_f32_16x16x32_bf16 v[126:129], v[164:167], v[206:209], v[126:129]
	v_mfma_f32_16x16x32_bf16 v[114:117], v[138:141], v[218:221], v[114:117]
	v_mfma_f32_16x16x32_bf16 v[110:113], v[164:167], v[218:221], v[110:113]
	v_mfma_f32_16x16x32_bf16 v[98:101], v[138:141], v[226:229], v[98:101]
	v_mfma_f32_16x16x32_bf16 v[94:97], v[164:167], v[226:229], v[94:97]
	v_mfma_f32_16x16x32_bf16 v[82:85], v[138:141], v[234:237], v[82:85]
	v_mfma_f32_16x16x32_bf16 v[78:81], v[164:167], v[234:237], v[78:81]
	v_mfma_f32_16x16x32_bf16 v[122:125], v[168:171], v[202:205], v[122:125]
	v_mfma_f32_16x16x32_bf16 v[118:121], v[194:197], v[202:205], v[118:121]
	v_mfma_f32_16x16x32_bf16 v[106:109], v[168:171], v[210:213], v[106:109]
	v_mfma_f32_16x16x32_bf16 v[102:105], v[194:197], v[210:213], v[102:105]
	v_mfma_f32_16x16x32_bf16 v[90:93], v[168:171], v[222:225], v[90:93]
	v_mfma_f32_16x16x32_bf16 v[86:89], v[194:197], v[222:225], v[86:89]
	v_mfma_f32_16x16x32_bf16 v[74:77], v[168:171], v[230:233], v[74:77]
	v_mfma_f32_16x16x32_bf16 v[70:73], v[194:197], v[230:233], v[70:73]
	v_mfma_f32_16x16x32_bf16 v[122:125], v[172:175], v[206:209], v[122:125]
	v_mfma_f32_16x16x32_bf16 v[118:121], v[198:201], v[206:209], v[118:121]
	v_mfma_f32_16x16x32_bf16 v[106:109], v[172:175], v[218:221], v[106:109]
	v_mfma_f32_16x16x32_bf16 v[102:105], v[198:201], v[218:221], v[102:105]
	v_mfma_f32_16x16x32_bf16 v[90:93], v[172:175], v[226:229], v[90:93]
	v_mfma_f32_16x16x32_bf16 v[86:89], v[198:201], v[226:229], v[86:89]
	v_mfma_f32_16x16x32_bf16 v[74:77], v[172:175], v[234:237], v[74:77]
	v_mfma_f32_16x16x32_bf16 v[70:73], v[198:201], v[234:237], v[70:73]
	s_barrier
	s_add_i32 s43, s45, s60
	v_lshl_add_u64 v[156:157], s[54:55], 0, v[142:143]
	s_mov_b32 m0, s43
	ds_read_b128 v[202:205], v191 offset:16384
	ds_read_b128 v[206:209], v191 offset:17408
	ds_read_b128 v[210:213], v191 offset:18432
	ds_read_b128 v[218:221], v191 offset:19456
	ds_read_b128 v[222:225], v191 offset:20480
	ds_read_b128 v[226:229], v191 offset:21504
	ds_read_b128 v[230:233], v191 offset:22528
	ds_read_b128 v[234:237], v191 offset:23552
	global_load_lds_dwordx4 v[156:157], off
	s_add_i32 m0, s43, 0x2000
	s_add_u32 s70, s54, 0x40000
	v_lshl_add_u64 v[176:177], s[54:55], 0, v[146:147]
	s_addc_u32 s71, s55, 0
	s_add_i32 s35, s35, s60
	global_load_lds_dwordx4 v[176:177], off
	v_lshl_add_u64 v[238:239], s[70:71], 0, v[142:143]
	s_mov_b32 m0, s35
	v_lshl_add_u64 v[240:241], s[56:57], 0, v[144:145]
	global_load_lds_dwordx4 v[238:239], off
	v_lshl_add_u64 v[238:239], s[70:71], 0, v[146:147]
	s_add_i32 m0, s35, 0x2000
	s_nop 0
	global_load_lds_dwordx4 v[238:239], off
	v_lshl_add_u64 v[238:239], s[56:57], 0, v[2:3]
	s_mov_b32 m0, s61
	s_nop 0
	global_load_lds_dwordx4 v[238:239], off
	s_mov_b32 m0, s62
	s_nop 0
	global_load_lds_dwordx4 v[240:241], off
	s_waitcnt vmcnt(8)
	s_waitcnt lgkmcnt(0)
	s_barrier
; #define PG8_STAGE(bufoff, gbase, voff) do { _Pragma("unroll") for (int _i = 0; _i < 2; ++_i) \
;         __builtin_amdgcn_global_load_lds((const unsigned*)((const char*)(gbase) + (voff)[_i]), (PG8_LAS unsigned*)(lds + (bufoff) + ldsw + _i * 8192), 16, 0, 0); } while (0)
; #define PG8_LDA(dst, b, h) do { _Pragma("unroll") for (int m = 0; m < 4; ++m) _Pragma("unroll") for (int k = 0; k < 2; ++k) dst[m][k] = *(const PG8_LAS bf16x8*)(lds + PG8_SA(b, h) + aoff + m * 2048 + k * 1024); } while (0)
; #define PG8_LDB(dst, b, h) do { _Pragma("unroll") for (int n = 0; n < 2; ++n) _Pragma("unroll") for (int k = 0; k < 2; ++k) dst[n][k] = *(const PG8_LAS bf16x8*)(lds + PG8_SB(b, h) + boff + n * 2048 + k * 1024); } while (0)
; #define PG8_MMA(ai, bj, At, Bt) do { __builtin_amdgcn_s_setprio(1); _Pragma("unroll") for (int m = 0; m < 4; ++m) _Pragma("unroll") for (int n = 0; n < 2; ++n) _Pragma("unroll") for (int k = 0; k < 2; ++k) \
;         acc[ai][bj][m][n] = __builtin_amdgcn_mfma_f32_16x16x32_bf16(Bt[n][k], At[m][k], acc[ai][bj][m][n], 0, 0, 0); __builtin_amdgcn_s_setprio(0); } while (0)
; #define PG8_WAIT_V(n) asm volatile("s_waitcnt vmcnt(" #n ")" ::: "memory")
; #define PG8_WAIT_L(n) asm volatile("s_waitcnt lgkmcnt(" #n ")" ::: "memory")
; #define PG8_BAR __builtin_amdgcn_s_barrier()
; #define PG8_SCHED __builtin_amdgcn_sched_barrier(0)
; template <class Epi, class Sched, bool ALIGN_EPI = false, bool SP2 = false>
; __device__ __forceinline__ void gemm_phase(PG8_LAS unsigned char* lds, const Gemm g, const Sched& S, const Epi& E, const int tid) {
;     ...
;             PG8_WAIT_V(8); PG8_WAIT_L(0); PG8_BAR; PG8_MMA(1, 0, At, B0); PG8_MMA(1, 1, At, B1); PG8_BAR; PG8_SCHED;
;             PG8_LDB(B0, 1, 0); PG8_LDB(B1, 1, 1); PG8_SCHED; PG8_LDA(At, 1, 0); PG8_STAGE(PG8_SA(0, 1), a2 + hstep, voffA);
;             PG8_WAIT_V(8); PG8_WAIT_L(0); PG8_BAR; PG8_MMA(0, 0, At, B0); PG8_MMA(0, 1, At, B1); PG8_BAR; PG8_SCHED;
	s_waitcnt lgkmcnt(0)
	v_mfma_f32_16x16x32_bf16 v[66:69], v[134:137], v[202:205], v[66:69]
	v_mfma_f32_16x16x32_bf16 v[62:65], v[152:155], v[202:205], v[62:65]
	v_mfma_f32_16x16x32_bf16 v[50:53], v[134:137], v[210:213], v[50:53]
	v_mfma_f32_16x16x32_bf16 v[46:49], v[152:155], v[210:213], v[46:49]
	v_mfma_f32_16x16x32_bf16 v[34:37], v[134:137], v[222:225], v[34:37]
	v_mfma_f32_16x16x32_bf16 v[30:33], v[152:155], v[222:225], v[30:33]
	v_mfma_f32_16x16x32_bf16 v[18:21], v[134:137], v[230:233], v[18:21]
	v_mfma_f32_16x16x32_bf16 v[14:17], v[152:155], v[230:233], v[14:17]
	v_mfma_f32_16x16x32_bf16 v[66:69], v[138:141], v[206:209], v[66:69]
	v_mfma_f32_16x16x32_bf16 v[62:65], v[164:167], v[206:209], v[62:65]
	v_mfma_f32_16x16x32_bf16 v[50:53], v[138:141], v[218:221], v[50:53]
	v_mfma_f32_16x16x32_bf16 v[46:49], v[164:167], v[218:221], v[46:49]
	v_mfma_f32_16x16x32_bf16 v[34:37], v[138:141], v[226:229], v[34:37]
	v_mfma_f32_16x16x32_bf16 v[30:33], v[164:167], v[226:229], v[30:33]
	v_mfma_f32_16x16x32_bf16 v[18:21], v[138:141], v[234:237], v[18:21]
	v_mfma_f32_16x16x32_bf16 v[14:17], v[164:167], v[234:237], v[14:17]
	v_mfma_f32_16x16x32_bf16 v[58:61], v[168:171], v[202:205], v[58:61]
	v_mfma_f32_16x16x32_bf16 v[54:57], v[194:197], v[202:205], v[54:57]
	v_mfma_f32_16x16x32_bf16 v[42:45], v[168:171], v[210:213], v[42:45]
	v_mfma_f32_16x16x32_bf16 v[38:41], v[194:197], v[210:213], v[38:41]
	v_mfma_f32_16x16x32_bf16 v[26:29], v[168:171], v[222:225], v[26:29]
	v_mfma_f32_16x16x32_bf16 v[22:25], v[194:197], v[222:225], v[22:25]
	v_mfma_f32_16x16x32_bf16 v[10:13], v[168:171], v[230:233], v[10:13]
	v_mfma_f32_16x16x32_bf16 v[6:9], v[194:197], v[230:233], v[6:9]
	v_mfma_f32_16x16x32_bf16 v[58:61], v[172:175], v[206:209], v[58:61]
	v_mfma_f32_16x16x32_bf16 v[54:57], v[198:201], v[206:209], v[54:57]
	v_mfma_f32_16x16x32_bf16 v[42:45], v[172:175], v[218:221], v[42:45]
	v_mfma_f32_16x16x32_bf16 v[38:41], v[198:201], v[218:221], v[38:41]
	v_mfma_f32_16x16x32_bf16 v[26:29], v[172:175], v[226:229], v[26:29]
	v_mfma_f32_16x16x32_bf16 v[22:25], v[198:201], v[226:229], v[22:25]
	v_mfma_f32_16x16x32_bf16 v[10:13], v[172:175], v[234:237], v[10:13]
	v_mfma_f32_16x16x32_bf16 v[6:9], v[198:201], v[234:237], v[6:9]
	s_barrier
	s_add_i32 s35, 0, 0x18000
	v_add_u32_e32 v160, s35, v5
	s_add_i32 s43, 0, 0x1c000
	ds_read_b128 v[134:137], v160
	ds_read_b128 v[138:141], v160 offset:1024
	ds_read_b128 v[152:155], v160 offset:2048
	ds_read_b128 v[164:167], v160 offset:3072
	v_add_u32_e32 v160, s43, v5
	ds_read_b128 v[168:171], v160
	ds_read_b128 v[172:175], v160 offset:1024
	ds_read_b128 v[194:197], v160 offset:2048
	ds_read_b128 v[198:201], v160 offset:3072
	s_add_u32 s56, s56, 0x40000
	s_addc_u32 s57, s57, 0
	s_mov_b32 m0, s63
	v_lshl_add_u64 v[242:243], s[56:57], 0, v[2:3]
	ds_read_b128 v[202:205], v191 offset:32768
	ds_read_b128 v[206:209], v191 offset:33792
	ds_read_b128 v[210:213], v191 offset:34816
	ds_read_b128 v[218:221], v191 offset:35840
	ds_read_b128 v[222:225], v191 offset:36864
	ds_read_b128 v[226:229], v191 offset:37888
	ds_read_b128 v[230:233], v191 offset:38912
	ds_read_b128 v[234:237], v191 offset:39936
	global_load_lds_dwordx4 v[242:243], off
	v_lshl_add_u64 v[242:243], s[56:57], 0, v[144:145]
	s_mov_b32 m0, s64
	s_nop 0
	global_load_lds_dwordx4 v[242:243], off
	s_waitcnt vmcnt(8)
	s_waitcnt lgkmcnt(0)
	s_barrier
	s_waitcnt lgkmcnt(0)
	v_mfma_f32_16x16x32_bf16 v[130:133], v[134:137], v[202:205], v[130:133]
	v_mfma_f32_16x16x32_bf16 v[126:129], v[152:155], v[202:205], v[126:129]
	v_mfma_f32_16x16x32_bf16 v[114:117], v[134:137], v[210:213], v[114:117]
	v_mfma_f32_16x16x32_bf16 v[110:113], v[152:155], v[210:213], v[110:113]
	v_mfma_f32_16x16x32_bf16 v[98:101], v[134:137], v[222:225], v[98:101]
	v_mfma_f32_16x16x32_bf16 v[94:97], v[152:155], v[222:225], v[94:97]
	v_mfma_f32_16x16x32_bf16 v[82:85], v[134:137], v[230:233], v[82:85]
	v_mfma_f32_16x16x32_bf16 v[78:81], v[152:155], v[230:233], v[78:81]
	v_mfma_f32_16x16x32_bf16 v[130:133], v[138:141], v[206:209], v[130:133]
	v_mfma_f32_16x16x32_bf16 v[126:129], v[164:167], v[206:209], v[126:129]
	v_mfma_f32_16x16x32_bf16 v[114:117], v[138:141], v[218:221], v[114:117]
	v_mfma_f32_16x16x32_bf16 v[110:113], v[164:167], v[218:221], v[110:113]
	v_mfma_f32_16x16x32_bf16 v[98:101], v[138:141], v[226:229], v[98:101]
	v_mfma_f32_16x16x32_bf16 v[94:97], v[164:167], v[226:229], v[94:97]
	v_mfma_f32_16x16x32_bf16 v[82:85], v[138:141], v[234:237], v[82:85]
	v_mfma_f32_16x16x32_bf16 v[78:81], v[164:167], v[234:237], v[78:81]
	v_mfma_f32_16x16x32_bf16 v[122:125], v[168:171], v[202:205], v[122:125]
	v_mfma_f32_16x16x32_bf16 v[118:121], v[194:197], v[202:205], v[118:121]
	v_mfma_f32_16x16x32_bf16 v[106:109], v[168:171], v[210:213], v[106:109]
	v_mfma_f32_16x16x32_bf16 v[102:105], v[194:197], v[210:213], v[102:105]
	v_mfma_f32_16x16x32_bf16 v[90:93], v[168:171], v[222:225], v[90:93]
	v_mfma_f32_16x16x32_bf16 v[86:89], v[194:197], v[222:225], v[86:89]
	v_mfma_f32_16x16x32_bf16 v[74:77], v[168:171], v[230:233], v[74:77]
	v_mfma_f32_16x16x32_bf16 v[70:73], v[194:197], v[230:233], v[70:73]
	v_mfma_f32_16x16x32_bf16 v[122:125], v[172:175], v[206:209], v[122:125]
	v_mfma_f32_16x16x32_bf16 v[118:121], v[198:201], v[206:209], v[118:121]
	v_mfma_f32_16x16x32_bf16 v[106:109], v[172:175], v[218:221], v[106:109]
	v_mfma_f32_16x16x32_bf16 v[102:105], v[198:201], v[218:221], v[102:105]
	v_mfma_f32_16x16x32_bf16 v[90:93], v[172:175], v[226:229], v[90:93]
	v_mfma_f32_16x16x32_bf16 v[86:89], v[198:201], v[226:229], v[86:89]
	v_mfma_f32_16x16x32_bf16 v[74:77], v[172:175], v[234:237], v[74:77]
	v_mfma_f32_16x16x32_bf16 v[70:73], v[198:201], v[234:237], v[70:73]
	s_barrier
; #define PG8_STAGE(bufoff, gbase, voff) do { _Pragma("unroll") for (int _i = 0; _i < 2; ++_i) \
;         __builtin_amdgcn_global_load_lds((const unsigned*)((const char*)(gbase) + (voff)[_i]), (PG8_LAS unsigned*)(lds + (bufoff) + ldsw + _i * 8192), 16, 0, 0); } while (0)
; #define PG8_LDA(dst, b, h) do { _Pragma("unroll") for (int m = 0; m < 4; ++m) _Pragma("unroll") for (int k = 0; k < 2; ++k) dst[m][k] = *(const PG8_LAS bf16x8*)(lds + PG8_SA(b, h) + aoff + m * 2048 + k * 1024); } while (0)
; #define PG8_MMA(ai, bj, At, Bt) do { __builtin_amdgcn_s_setprio(1); _Pragma("unroll") for (int m = 0; m < 4; ++m) _Pragma("unroll") for (int n = 0; n < 2; ++n) _Pragma("unroll") for (int k = 0; k < 2; ++k) \
;         acc[ai][bj][m][n] = __builtin_amdgcn_mfma_f32_16x16x32_bf16(Bt[n][k], At[m][k], acc[ai][bj][m][n], 0, 0, 0); __builtin_amdgcn_s_setprio(0); } while (0)
; #define PG8_WAIT_V(n) asm volatile("s_waitcnt vmcnt(" #n ")" ::: "memory")
; #define PG8_WAIT_L(n) asm volatile("s_waitcnt lgkmcnt(" #n ")" ::: "memory")
; #define PG8_BAR __builtin_amdgcn_s_barrier()
; #define PG8_SCHED __builtin_amdgcn_sched_barrier(0)
; template <class Epi, class Sched, bool ALIGN_EPI = false, bool SP2 = false>
; __device__ __forceinline__ void gemm_phase(PG8_LAS unsigned char* lds, const Gemm g, const Sched& S, const Epi& E, const int tid) {
;     ...
;             PG8_LDA(At, 1, 1); PG8_STAGE(PG8_SB(1, 0), b3, voffB); PG8_STAGE(PG8_SB(1, 1), b3 + hstep, voffB); PG8_STAGE(PG8_SA(1, 0), a3, voffA);
;             PG8_WAIT_V(8); PG8_WAIT_L(0); PG8_BAR; PG8_MMA(1, 0, At, B0); PG8_MMA(1, 1, At, B1); PG8_BAR; PG8_SCHED;
;     ...
;         if constexpr (ALIGN_EPI) { if (wr == 0) PG8_BAR; }
	s_add_i32 s35, s35, s60
	v_lshl_add_u64 v[156:157], v[156:157], 0, s[16:17]
	s_mov_b32 m0, s35
	ds_read_b128 v[202:205], v191 offset:49152
	ds_read_b128 v[206:209], v191 offset:50176
	ds_read_b128 v[210:213], v191 offset:51200
	ds_read_b128 v[218:221], v191 offset:52224
	ds_read_b128 v[222:225], v191 offset:53248
	ds_read_b128 v[226:229], v191 offset:54272
	ds_read_b128 v[230:233], v191 offset:55296
	ds_read_b128 v[234:237], v191 offset:56320
	global_load_lds_dwordx4 v[156:157], off
	s_add_i32 m0, s35, 0x2000
	s_add_u32 s54, s54, 0x40080
	v_lshl_add_u64 v[156:157], v[176:177], 0, s[16:17]
	s_addc_u32 s55, s55, 0
	s_add_i32 s35, s43, s60
	global_load_lds_dwordx4 v[156:157], off
	v_lshl_add_u64 v[156:157], s[54:55], 0, v[142:143]
	s_mov_b32 m0, s35
	s_nop 0
	global_load_lds_dwordx4 v[156:157], off
	v_lshl_add_u64 v[156:157], s[54:55], 0, v[146:147]
	s_add_i32 m0, s35, 0x2000
	s_nop 0
	global_load_lds_dwordx4 v[156:157], off
	v_lshl_add_u64 v[156:157], v[238:239], 0, s[16:17]
	s_mov_b32 m0, s20
	s_nop 0
	global_load_lds_dwordx4 v[156:157], off
	v_lshl_add_u64 v[156:157], v[240:241], 0, s[16:17]
	s_mov_b32 m0, s65
	s_nop 0
	global_load_lds_dwordx4 v[156:157], off
	s_waitcnt vmcnt(8)
	s_waitcnt lgkmcnt(0)
	s_barrier
	s_waitcnt lgkmcnt(0)
	v_mfma_f32_16x16x32_bf16 v[66:69], v[134:137], v[202:205], v[66:69]
	v_mfma_f32_16x16x32_bf16 v[62:65], v[152:155], v[202:205], v[62:65]
	v_mfma_f32_16x16x32_bf16 v[50:53], v[134:137], v[210:213], v[50:53]
	v_mfma_f32_16x16x32_bf16 v[46:49], v[152:155], v[210:213], v[46:49]
	v_mfma_f32_16x16x32_bf16 v[34:37], v[134:137], v[222:225], v[34:37]
	v_mfma_f32_16x16x32_bf16 v[30:33], v[152:155], v[222:225], v[30:33]
	v_mfma_f32_16x16x32_bf16 v[18:21], v[134:137], v[230:233], v[18:21]
	v_mfma_f32_16x16x32_bf16 v[14:17], v[152:155], v[230:233], v[14:17]
	v_mfma_f32_16x16x32_bf16 v[66:69], v[138:141], v[206:209], v[66:69]
	v_mfma_f32_16x16x32_bf16 v[62:65], v[164:167], v[206:209], v[62:65]
	v_mfma_f32_16x16x32_bf16 v[50:53], v[138:141], v[218:221], v[50:53]
	v_mfma_f32_16x16x32_bf16 v[46:49], v[164:167], v[218:221], v[46:49]
	v_mfma_f32_16x16x32_bf16 v[34:37], v[138:141], v[226:229], v[34:37]
	v_mfma_f32_16x16x32_bf16 v[30:33], v[164:167], v[226:229], v[30:33]
	v_mfma_f32_16x16x32_bf16 v[18:21], v[138:141], v[234:237], v[18:21]
	v_mfma_f32_16x16x32_bf16 v[14:17], v[164:167], v[234:237], v[14:17]
	v_mfma_f32_16x16x32_bf16 v[58:61], v[168:171], v[202:205], v[58:61]
	v_mfma_f32_16x16x32_bf16 v[54:57], v[194:197], v[202:205], v[54:57]
	v_mfma_f32_16x16x32_bf16 v[42:45], v[168:171], v[210:213], v[42:45]
	v_mfma_f32_16x16x32_bf16 v[38:41], v[194:197], v[210:213], v[38:41]
	v_mfma_f32_16x16x32_bf16 v[26:29], v[168:171], v[222:225], v[26:29]
	v_mfma_f32_16x16x32_bf16 v[22:25], v[194:197], v[222:225], v[22:25]
	v_mfma_f32_16x16x32_bf16 v[10:13], v[168:171], v[230:233], v[10:13]
	v_mfma_f32_16x16x32_bf16 v[6:9], v[194:197], v[230:233], v[6:9]
	v_mfma_f32_16x16x32_bf16 v[58:61], v[172:175], v[206:209], v[58:61]
	v_mfma_f32_16x16x32_bf16 v[54:57], v[198:201], v[206:209], v[54:57]
	v_mfma_f32_16x16x32_bf16 v[42:45], v[172:175], v[218:221], v[42:45]
	v_mfma_f32_16x16x32_bf16 v[38:41], v[198:201], v[218:221], v[38:41]
	v_mfma_f32_16x16x32_bf16 v[26:29], v[172:175], v[226:229], v[26:29]
	v_mfma_f32_16x16x32_bf16 v[22:25], v[198:201], v[226:229], v[22:25]
	v_mfma_f32_16x16x32_bf16 v[10:13], v[172:175], v[234:237], v[10:13]
	v_mfma_f32_16x16x32_bf16 v[6:9], v[198:201], v[234:237], v[6:9]
	s_barrier
	s_add_i32 s34, s34, 2
	s_add_u32 s52, s52, 0x100
	s_addc_u32 s53, s53, 0
	s_add_u32 s19, s19, 0x100
	s_addc_u32 s33, s33, 0
	s_cmp_gt_u32 s34, 13
	s_cbranch_scc0 .LBB0_94
	s_and_b64 vcc, exec, s[40:41]
	s_cbranch_vccz .LBB0_97
	s_barrier

; #define PG8_WAIT_V(n) asm volatile("s_waitcnt vmcnt(" #n ")" ::: "memory")
; #define PG8_BAR __builtin_amdgcn_s_barrier()
; template <class Epi, class Sched, bool ALIGN_EPI = false, bool SP2 = false>
; __device__ __forceinline__ void gemm_phase(PG8_LAS unsigned char* lds, const Gemm g, const Sched& S, const Epi& E, const int tid) {
;     ...
;     PG8_WAIT_V(0);
;     if constexpr (!ALIGN_EPI) { if (wr == 0) PG8_BAR; }
;     PG8_BAR;
; DI void xcd_barrier(const XcdBarrier& b) {
;     asm volatile("s_waitcnt vmcnt(0)" ::: "memory");
;     __syncthreads();
;     if (threadIdx.x == 0) {
;         unsigned* bar = b.bar;
;         __builtin_amdgcn_s_waitcnt(0);
;         unsigned nloc = b.st[0], nx = b.st[1];
;         if (nloc == 0u) { xcd_barrier_complete(bar, b.x, nloc, nx); b.st[0] = nloc; b.st[1] = nx; }
.LBB0_156:
	s_setprio 0
	s_waitcnt vmcnt(0)
	s_waitcnt vmcnt(0) lgkmcnt(0)
	s_barrier
	s_and_saveexec_b64 s[0:1], s[90:91]
	v_readlane_b32 s36, v252, 0
	s_xor_b64 s[2:3], exec, s[0:1]
	v_readlane_b32 s48, v252, 12
	v_readlane_b32 s49, v252, 13
	v_readlane_b32 s26, v253, 62
	s_movk_i32 s27, 0x90
	v_readlane_b32 s37, v252, 1
	v_readlane_b32 s38, v252, 2
	v_readlane_b32 s39, v252, 3
	v_readlane_b32 s40, v252, 4
	v_readlane_b32 s41, v252, 5
	v_readlane_b32 s42, v252, 6
	v_readlane_b32 s43, v252, 7
	v_readlane_b32 s44, v252, 8
	v_readlane_b32 s45, v252, 9
	v_readlane_b32 s46, v252, 10
	v_readlane_b32 s47, v252, 11
	v_readlane_b32 s50, v252, 14
	v_readlane_b32 s51, v252, 15
	s_cbranch_execz .LBB0_209
	v_readlane_b32 s0, v253, 60
	s_waitcnt vmcnt(0) expcnt(0) lgkmcnt(0)
	s_nop 0
	v_mov_b32_e32 v1, s0
	ds_read_b32 v3, v1
	v_readlane_b32 s0, v253, 61
	s_waitcnt lgkmcnt(0)
	v_cmp_ne_u32_e32 vcc, 0, v3
	v_mov_b32_e32 v1, s0
	ds_read_b32 v2, v1
	s_cbranch_vccnz .LBB0_172
	s_mov_b32 s0, 1
	s_branch .LBB0_160

; #define PG8_LAS __attribute__((address_space(3)))
; #define LAUNDER() asm volatile("" : "+v"(tid), "+s"(bid), "+s"(nb))
; #define GSYNC() xcd_barrier(xbar)
;     __host__ __device__ bool next(int i, Unit& u) const {
;         const long L = (long)i * G + c; if (L >= nwg) return false;
;         int wgid = (int)L; { const int q = nwg / NXCD, r = nwg % NXCD, xcd = wgid % NXCD, off = wgid / NXCD; wgid = (xcd < r ? xcd * (q + 1) : r * (q + 1) + (xcd - r) * q) + off; }
; __global__ void __launch_bounds__(NT, 2) mega_fwd(Ctx c) {
;     ...
;             GSYNC();
;             LAUNDER();
;             if (l == 0) { pg8::EpiResB<false, false> E{xin, H2, DM, SSQ2, (PG8_LAS float*)(lds + 131072)}; run_gemm(lds, MIX, (const bf16*)(ws + WS_WOUT + l * SZ_WOUT), DM, DM, E, bid, nb, tid); }
.LBB0_476:
	s_or_b64 exec, exec, s[2:3]
	s_mov_b64 s[2:3], -1
	s_and_b64 vcc, exec, s[94:95]
	s_waitcnt lgkmcnt(0)
	s_barrier
	v_readfirstlane_b32 s98, v158
	s_nop 3
	s_lshr_b32 s98, s98, 6
	s_cmp_ge_u32 s98, 4
	s_cbranch_scc0 .Lprio_skip_1
	s_setprio 1
.Lprio_skip_1:
	s_cbranch_vccz .LBB0_522
	s_cmpk_lt_i32 s86, 0x100
	s_cselect_b64 s[2:3], -1, 0
	s_cmpk_gt_i32 s86, 0xff
	v_readfirstlane_b32 s0, v158
	s_cbranch_scc1 .LBB0_483
	s_ashr_i32 s1, s86, 31
	s_lshr_b32 s1, s1, 29
	s_add_i32 s1, s86, s1
	s_and_b32 s4, s1, -8
	s_sub_i32 s6, s86, s4
	s_cmp_gt_i32 s6, -1
	s_mov_b64 s[4:5], -1
	s_cbranch_scc0 .LBB0_480
	s_lshl_b32 s7, s6, 5
	s_mov_b64 s[4:5], 0

; #define PG8_STAGE(bufoff, gbase, voff) do { _Pragma("unroll") for (int _i = 0; _i < 2; ++_i) \
;         __builtin_amdgcn_global_load_lds((const unsigned*)((const char*)(gbase) + (voff)[_i]), (PG8_LAS unsigned*)(lds + (bufoff) + ldsw + _i * 8192), 16, 0, 0); } while (0)
; #define PG8_LDA(dst, b, h) do { _Pragma("unroll") for (int m = 0; m < 4; ++m) _Pragma("unroll") for (int k = 0; k < 2; ++k) dst[m][k] = *(const PG8_LAS bf16x8*)(lds + PG8_SA(b, h) + aoff + m * 2048 + k * 1024); } while (0)
; #define PG8_LDB(dst, b, h) do { _Pragma("unroll") for (int n = 0; n < 2; ++n) _Pragma("unroll") for (int k = 0; k < 2; ++k) dst[n][k] = *(const PG8_LAS bf16x8*)(lds + PG8_SB(b, h) + boff + n * 2048 + k * 1024); } while (0)
; #define PG8_MMA(ai, bj, At, Bt) do { __builtin_amdgcn_s_setprio(1); _Pragma("unroll") for (int m = 0; m < 4; ++m) _Pragma("unroll") for (int n = 0; n < 2; ++n) _Pragma("unroll") for (int k = 0; k < 2; ++k) \
;         acc[ai][bj][m][n] = __builtin_amdgcn_mfma_f32_16x16x32_bf16(Bt[n][k], At[m][k], acc[ai][bj][m][n], 0, 0, 0); __builtin_amdgcn_s_setprio(0); } while (0)
; #define PG8_WAIT_V(n) asm volatile("s_waitcnt vmcnt(" #n ")" ::: "memory")
; #define PG8_WAIT_L(n) asm volatile("s_waitcnt lgkmcnt(" #n ")" ::: "memory")
; #define PG8_BAR __builtin_amdgcn_s_barrier()
; #define PG8_SCHED __builtin_amdgcn_sched_barrier(0)
; template <class Epi, class Sched, bool ALIGN_EPI = false, bool SP2 = false>
; __device__ __forceinline__ void gemm_phase(PG8_LAS unsigned char* lds, const Gemm g, const Sched& S, const Epi& E, const int tid) {
;     ...
;             PG8_LDB(B0, 0, 0); PG8_LDB(B1, 0, 1); PG8_SCHED; PG8_LDA(At, 0, 0); PG8_STAGE(PG8_SA(1, 1), a1 + hstep, voffA);
;             PG8_WAIT_V(8); PG8_WAIT_L(0); PG8_BAR; PG8_MMA(0, 0, At, B0); PG8_MMA(0, 1, At, B1); PG8_BAR; PG8_SCHED;
;             PG8_LDA(At, 0, 1); PG8_STAGE(PG8_SB(0, 0), b2, voffB); PG8_STAGE(PG8_SB(0, 1), b2 + hstep, voffB); PG8_STAGE(PG8_SA(0, 0), a2, voffA);
;             PG8_WAIT_V(8); PG8_WAIT_L(0); PG8_BAR; PG8_MMA(1, 0, At, B0); PG8_MMA(1, 1, At, B1); PG8_BAR; PG8_SCHED;
.LBB0_496:
	s_add_u32 s26, s44, 0xfffc0080
	s_addc_u32 s27, s45, -1
	s_add_i32 s34, 0, 0x10000
	s_cmp_eq_u32 s33, 12
	s_cselect_b32 s49, s0, s27
	s_cselect_b32 s48, s1, s26
	v_add_u32_e32 v148, s34, v5
	s_cselect_b32 s47, s13, s19
	s_cselect_b32 s46, s15, s18
	s_add_i32 s26, 0, 0x14000
	ds_read_b128 v[144:147], v148
	ds_read_b128 v[174:177], v148 offset:1024
	ds_read_b128 v[178:181], v148 offset:2048
	ds_read_b128 v[182:185], v148 offset:3072
	v_add_u32_e32 v148, s26, v5
	ds_read_b128 v[186:189], v148
	ds_read_b128 v[190:193], v148 offset:1024
	ds_read_b128 v[194:197], v148 offset:2048
	ds_read_b128 v[198:201], v148 offset:3072
	v_lshl_add_u64 v[148:149], s[44:45], 0, v[140:141]
	s_add_i32 m0, s50, 0xc000
	ds_read_b128 v[202:205], v167
	ds_read_b128 v[206:209], v167 offset:1024
	ds_read_b128 v[210:213], v167 offset:2048
	ds_read_b128 v[218:221], v167 offset:3072
	ds_read_b128 v[222:225], v167 offset:4096
	ds_read_b128 v[226:229], v167 offset:5120
	ds_read_b128 v[230:233], v167 offset:6144
	ds_read_b128 v[234:237], v167 offset:7168
	global_load_lds_dwordx4 v[148:149], off
	v_lshl_add_u64 v[148:149], s[44:45], 0, v[142:143]
	s_add_i32 m0, s50, 0xe000
	s_nop 0
	global_load_lds_dwordx4 v[148:149], off
	s_waitcnt vmcnt(8)
	s_waitcnt lgkmcnt(0)
	s_barrier
	s_waitcnt lgkmcnt(0)
	v_mfma_f32_16x16x32_bf16 v[130:133], v[144:147], v[202:205], v[130:133]
	v_mfma_f32_16x16x32_bf16 v[126:129], v[178:181], v[202:205], v[126:129]
	v_mfma_f32_16x16x32_bf16 v[114:117], v[144:147], v[210:213], v[114:117]
	v_mfma_f32_16x16x32_bf16 v[110:113], v[178:181], v[210:213], v[110:113]
	v_mfma_f32_16x16x32_bf16 v[98:101], v[144:147], v[222:225], v[98:101]
	v_mfma_f32_16x16x32_bf16 v[94:97], v[178:181], v[222:225], v[94:97]
	v_mfma_f32_16x16x32_bf16 v[82:85], v[144:147], v[230:233], v[82:85]
	v_mfma_f32_16x16x32_bf16 v[78:81], v[178:181], v[230:233], v[78:81]
	v_mfma_f32_16x16x32_bf16 v[130:133], v[174:177], v[206:209], v[130:133]
	v_mfma_f32_16x16x32_bf16 v[126:129], v[182:185], v[206:209], v[126:129]
	v_mfma_f32_16x16x32_bf16 v[114:117], v[174:177], v[218:221], v[114:117]
	v_mfma_f32_16x16x32_bf16 v[110:113], v[182:185], v[218:221], v[110:113]
	v_mfma_f32_16x16x32_bf16 v[98:101], v[174:177], v[226:229], v[98:101]
	v_mfma_f32_16x16x32_bf16 v[94:97], v[182:185], v[226:229], v[94:97]
	v_mfma_f32_16x16x32_bf16 v[82:85], v[174:177], v[234:237], v[82:85]
	v_mfma_f32_16x16x32_bf16 v[78:81], v[182:185], v[234:237], v[78:81]
	v_mfma_f32_16x16x32_bf16 v[122:125], v[186:189], v[202:205], v[122:125]
	v_mfma_f32_16x16x32_bf16 v[118:121], v[194:197], v[202:205], v[118:121]
	v_mfma_f32_16x16x32_bf16 v[106:109], v[186:189], v[210:213], v[106:109]
	v_mfma_f32_16x16x32_bf16 v[102:105], v[194:197], v[210:213], v[102:105]
	v_mfma_f32_16x16x32_bf16 v[90:93], v[186:189], v[222:225], v[90:93]
	v_mfma_f32_16x16x32_bf16 v[86:89], v[194:197], v[222:225], v[86:89]
	v_mfma_f32_16x16x32_bf16 v[74:77], v[186:189], v[230:233], v[74:77]
	v_mfma_f32_16x16x32_bf16 v[70:73], v[194:197], v[230:233], v[70:73]
	v_mfma_f32_16x16x32_bf16 v[122:125], v[190:193], v[206:209], v[122:125]
	v_mfma_f32_16x16x32_bf16 v[118:121], v[198:201], v[206:209], v[118:121]
	v_mfma_f32_16x16x32_bf16 v[106:109], v[190:193], v[218:221], v[106:109]
	v_mfma_f32_16x16x32_bf16 v[102:105], v[198:201], v[218:221], v[102:105]
	v_mfma_f32_16x16x32_bf16 v[90:93], v[190:193], v[226:229], v[90:93]
	v_mfma_f32_16x16x32_bf16 v[86:89], v[198:201], v[226:229], v[86:89]
	v_mfma_f32_16x16x32_bf16 v[74:77], v[190:193], v[234:237], v[74:77]
	v_mfma_f32_16x16x32_bf16 v[70:73], v[198:201], v[234:237], v[70:73]
	s_barrier
	s_add_i32 s27, s34, s20
	v_lshl_add_u64 v[148:149], s[46:47], 0, v[134:135]
	s_mov_b32 m0, s27
	ds_read_b128 v[202:205], v167 offset:16384
	ds_read_b128 v[206:209], v167 offset:17408
	ds_read_b128 v[210:213], v167 offset:18432
	ds_read_b128 v[218:221], v167 offset:19456
	ds_read_b128 v[222:225], v167 offset:20480
	ds_read_b128 v[226:229], v167 offset:21504
	ds_read_b128 v[230:233], v167 offset:22528
	ds_read_b128 v[234:237], v167 offset:23552
	global_load_lds_dwordx4 v[148:149], off
	s_add_i32 m0, s27, 0x2000
	s_add_u32 s34, s46, 0x40000
	v_lshl_add_u64 v[160:161], s[46:47], 0, v[138:139]
	s_addc_u32 s35, s47, 0
	s_add_i32 s26, s26, s20
	global_load_lds_dwordx4 v[160:161], off
	v_lshl_add_u64 v[214:215], s[34:35], 0, v[134:135]
	s_mov_b32 m0, s26
	v_lshl_add_u64 v[238:239], s[48:49], 0, v[136:137]
	global_load_lds_dwordx4 v[214:215], off
	v_lshl_add_u64 v[214:215], s[34:35], 0, v[138:139]
	s_add_i32 m0, s26, 0x2000
	s_nop 0
	global_load_lds_dwordx4 v[214:215], off
	v_lshl_add_u64 v[214:215], s[48:49], 0, v[2:3]
	s_mov_b32 m0, s50
	s_nop 0
	global_load_lds_dwordx4 v[214:215], off
	s_mov_b32 m0, s51
	s_nop 0
	global_load_lds_dwordx4 v[238:239], off
	s_waitcnt vmcnt(8)
	s_waitcnt lgkmcnt(0)
	s_barrier
; #define PG8_STAGE(bufoff, gbase, voff) do { _Pragma("unroll") for (int _i = 0; _i < 2; ++_i) \
;         __builtin_amdgcn_global_load_lds((const unsigned*)((const char*)(gbase) + (voff)[_i]), (PG8_LAS unsigned*)(lds + (bufoff) + ldsw + _i * 8192), 16, 0, 0); } while (0)
; #define PG8_LDA(dst, b, h) do { _Pragma("unroll") for (int m = 0; m < 4; ++m) _Pragma("unroll") for (int k = 0; k < 2; ++k) dst[m][k] = *(const PG8_LAS bf16x8*)(lds + PG8_SA(b, h) + aoff + m * 2048 + k * 1024); } while (0)
; #define PG8_LDB(dst, b, h) do { _Pragma("unroll") for (int n = 0; n < 2; ++n) _Pragma("unroll") for (int k = 0; k < 2; ++k) dst[n][k] = *(const PG8_LAS bf16x8*)(lds + PG8_SB(b, h) + boff + n * 2048 + k * 1024); } while (0)
; #define PG8_MMA(ai, bj, At, Bt) do { __builtin_amdgcn_s_setprio(1); _Pragma("unroll") for (int m = 0; m < 4; ++m) _Pragma("unroll") for (int n = 0; n < 2; ++n) _Pragma("unroll") for (int k = 0; k < 2; ++k) \
;         acc[ai][bj][m][n] = __builtin_amdgcn_mfma_f32_16x16x32_bf16(Bt[n][k], At[m][k], acc[ai][bj][m][n], 0, 0, 0); __builtin_amdgcn_s_setprio(0); } while (0)
; #define PG8_WAIT_V(n) asm volatile("s_waitcnt vmcnt(" #n ")" ::: "memory")
; #define PG8_WAIT_L(n) asm volatile("s_waitcnt lgkmcnt(" #n ")" ::: "memory")
; #define PG8_BAR __builtin_amdgcn_s_barrier()
; #define PG8_SCHED __builtin_amdgcn_sched_barrier(0)
; template <class Epi, class Sched, bool ALIGN_EPI = false, bool SP2 = false>
; __device__ __forceinline__ void gemm_phase(PG8_LAS unsigned char* lds, const Gemm g, const Sched& S, const Epi& E, const int tid) {
;     ...
;             PG8_WAIT_V(8); PG8_WAIT_L(0); PG8_BAR; PG8_MMA(1, 0, At, B0); PG8_MMA(1, 1, At, B1); PG8_BAR; PG8_SCHED;
;             PG8_LDB(B0, 1, 0); PG8_LDB(B1, 1, 1); PG8_SCHED; PG8_LDA(At, 1, 0); PG8_STAGE(PG8_SA(0, 1), a2 + hstep, voffA);
;             PG8_WAIT_V(8); PG8_WAIT_L(0); PG8_BAR; PG8_MMA(0, 0, At, B0); PG8_MMA(0, 1, At, B1); PG8_BAR; PG8_SCHED;
	s_waitcnt lgkmcnt(0)
	v_mfma_f32_16x16x32_bf16 v[66:69], v[144:147], v[202:205], v[66:69]
	v_mfma_f32_16x16x32_bf16 v[62:65], v[178:181], v[202:205], v[62:65]
	v_mfma_f32_16x16x32_bf16 v[50:53], v[144:147], v[210:213], v[50:53]
	v_mfma_f32_16x16x32_bf16 v[46:49], v[178:181], v[210:213], v[46:49]
	v_mfma_f32_16x16x32_bf16 v[34:37], v[144:147], v[222:225], v[34:37]
	v_mfma_f32_16x16x32_bf16 v[30:33], v[178:181], v[222:225], v[30:33]
	v_mfma_f32_16x16x32_bf16 v[18:21], v[144:147], v[230:233], v[18:21]
	v_mfma_f32_16x16x32_bf16 v[14:17], v[178:181], v[230:233], v[14:17]
	v_mfma_f32_16x16x32_bf16 v[66:69], v[174:177], v[206:209], v[66:69]
	v_mfma_f32_16x16x32_bf16 v[62:65], v[182:185], v[206:209], v[62:65]
	v_mfma_f32_16x16x32_bf16 v[50:53], v[174:177], v[218:221], v[50:53]
	v_mfma_f32_16x16x32_bf16 v[46:49], v[182:185], v[218:221], v[46:49]
	v_mfma_f32_16x16x32_bf16 v[34:37], v[174:177], v[226:229], v[34:37]
	v_mfma_f32_16x16x32_bf16 v[30:33], v[182:185], v[226:229], v[30:33]
	v_mfma_f32_16x16x32_bf16 v[18:21], v[174:177], v[234:237], v[18:21]
	v_mfma_f32_16x16x32_bf16 v[14:17], v[182:185], v[234:237], v[14:17]
	v_mfma_f32_16x16x32_bf16 v[58:61], v[186:189], v[202:205], v[58:61]
	v_mfma_f32_16x16x32_bf16 v[54:57], v[194:197], v[202:205], v[54:57]
	v_mfma_f32_16x16x32_bf16 v[42:45], v[186:189], v[210:213], v[42:45]
	v_mfma_f32_16x16x32_bf16 v[38:41], v[194:197], v[210:213], v[38:41]
	v_mfma_f32_16x16x32_bf16 v[26:29], v[186:189], v[222:225], v[26:29]
	v_mfma_f32_16x16x32_bf16 v[22:25], v[194:197], v[222:225], v[22:25]
	v_mfma_f32_16x16x32_bf16 v[10:13], v[186:189], v[230:233], v[10:13]
	v_mfma_f32_16x16x32_bf16 v[6:9], v[194:197], v[230:233], v[6:9]
	v_mfma_f32_16x16x32_bf16 v[58:61], v[190:193], v[206:209], v[58:61]
	v_mfma_f32_16x16x32_bf16 v[54:57], v[198:201], v[206:209], v[54:57]
	v_mfma_f32_16x16x32_bf16 v[42:45], v[190:193], v[218:221], v[42:45]
	v_mfma_f32_16x16x32_bf16 v[38:41], v[198:201], v[218:221], v[38:41]
	v_mfma_f32_16x16x32_bf16 v[26:29], v[190:193], v[226:229], v[26:29]
	v_mfma_f32_16x16x32_bf16 v[22:25], v[198:201], v[226:229], v[22:25]
	v_mfma_f32_16x16x32_bf16 v[10:13], v[190:193], v[234:237], v[10:13]
	v_mfma_f32_16x16x32_bf16 v[6:9], v[198:201], v[234:237], v[6:9]
	s_barrier
	s_add_i32 s26, 0, 0x18000
	s_add_i32 s27, 0, 0x1c000
	v_add_u32_e32 v182, s26, v5
	v_add_u32_e32 v198, s27, v5
	ds_read_b128 v[144:147], v182
	ds_read_b128 v[174:177], v182 offset:1024
	ds_read_b128 v[178:181], v182 offset:2048
	ds_read_b128 v[182:185], v182 offset:3072
	ds_read_b128 v[186:189], v198
	ds_read_b128 v[190:193], v198 offset:1024
	ds_read_b128 v[194:197], v198 offset:2048
	ds_read_b128 v[198:201], v198 offset:3072
	s_add_u32 s34, s48, 0x40000
	s_addc_u32 s35, s49, 0
	s_mov_b32 m0, s52
	v_lshl_add_u64 v[240:241], s[34:35], 0, v[2:3]
	ds_read_b128 v[202:205], v167 offset:32768
	ds_read_b128 v[206:209], v167 offset:33792
	ds_read_b128 v[210:213], v167 offset:34816
	ds_read_b128 v[218:221], v167 offset:35840
	ds_read_b128 v[222:225], v167 offset:36864
	ds_read_b128 v[226:229], v167 offset:37888
	ds_read_b128 v[230:233], v167 offset:38912
	ds_read_b128 v[234:237], v167 offset:39936
	global_load_lds_dwordx4 v[240:241], off
	v_lshl_add_u64 v[240:241], s[34:35], 0, v[136:137]
	s_mov_b32 m0, s53
	s_nop 0
	global_load_lds_dwordx4 v[240:241], off
	s_waitcnt vmcnt(8)
	s_waitcnt lgkmcnt(0)
	s_barrier
	s_waitcnt lgkmcnt(0)
	v_mfma_f32_16x16x32_bf16 v[130:133], v[144:147], v[202:205], v[130:133]
	v_mfma_f32_16x16x32_bf16 v[126:129], v[178:181], v[202:205], v[126:129]
	v_mfma_f32_16x16x32_bf16 v[114:117], v[144:147], v[210:213], v[114:117]
	v_mfma_f32_16x16x32_bf16 v[110:113], v[178:181], v[210:213], v[110:113]
	v_mfma_f32_16x16x32_bf16 v[98:101], v[144:147], v[222:225], v[98:101]
	v_mfma_f32_16x16x32_bf16 v[94:97], v[178:181], v[222:225], v[94:97]
	v_mfma_f32_16x16x32_bf16 v[82:85], v[144:147], v[230:233], v[82:85]
	v_mfma_f32_16x16x32_bf16 v[78:81], v[178:181], v[230:233], v[78:81]
	v_mfma_f32_16x16x32_bf16 v[130:133], v[174:177], v[206:209], v[130:133]
	v_mfma_f32_16x16x32_bf16 v[126:129], v[182:185], v[206:209], v[126:129]
	v_mfma_f32_16x16x32_bf16 v[114:117], v[174:177], v[218:221], v[114:117]
	v_mfma_f32_16x16x32_bf16 v[110:113], v[182:185], v[218:221], v[110:113]
	v_mfma_f32_16x16x32_bf16 v[98:101], v[174:177], v[226:229], v[98:101]
	v_mfma_f32_16x16x32_bf16 v[94:97], v[182:185], v[226:229], v[94:97]
	v_mfma_f32_16x16x32_bf16 v[82:85], v[174:177], v[234:237], v[82:85]
	v_mfma_f32_16x16x32_bf16 v[78:81], v[182:185], v[234:237], v[78:81]
	v_mfma_f32_16x16x32_bf16 v[122:125], v[186:189], v[202:205], v[122:125]
	v_mfma_f32_16x16x32_bf16 v[118:121], v[194:197], v[202:205], v[118:121]
	v_mfma_f32_16x16x32_bf16 v[106:109], v[186:189], v[210:213], v[106:109]
	v_mfma_f32_16x16x32_bf16 v[102:105], v[194:197], v[210:213], v[102:105]
	v_mfma_f32_16x16x32_bf16 v[90:93], v[186:189], v[222:225], v[90:93]
	v_mfma_f32_16x16x32_bf16 v[86:89], v[194:197], v[222:225], v[86:89]
	v_mfma_f32_16x16x32_bf16 v[74:77], v[186:189], v[230:233], v[74:77]
	v_mfma_f32_16x16x32_bf16 v[70:73], v[194:197], v[230:233], v[70:73]
	v_mfma_f32_16x16x32_bf16 v[122:125], v[190:193], v[206:209], v[122:125]
	v_mfma_f32_16x16x32_bf16 v[118:121], v[198:201], v[206:209], v[118:121]
	v_mfma_f32_16x16x32_bf16 v[106:109], v[190:193], v[218:221], v[106:109]
	v_mfma_f32_16x16x32_bf16 v[102:105], v[198:201], v[218:221], v[102:105]
	v_mfma_f32_16x16x32_bf16 v[90:93], v[190:193], v[226:229], v[90:93]
	v_mfma_f32_16x16x32_bf16 v[86:89], v[198:201], v[226:229], v[86:89]
	v_mfma_f32_16x16x32_bf16 v[74:77], v[190:193], v[234:237], v[74:77]
	v_mfma_f32_16x16x32_bf16 v[70:73], v[198:201], v[234:237], v[70:73]
	s_barrier
; #define PG8_STAGE(bufoff, gbase, voff) do { _Pragma("unroll") for (int _i = 0; _i < 2; ++_i) \
;         __builtin_amdgcn_global_load_lds((const unsigned*)((const char*)(gbase) + (voff)[_i]), (PG8_LAS unsigned*)(lds + (bufoff) + ldsw + _i * 8192), 16, 0, 0); } while (0)
; #define PG8_LDA(dst, b, h) do { _Pragma("unroll") for (int m = 0; m < 4; ++m) _Pragma("unroll") for (int k = 0; k < 2; ++k) dst[m][k] = *(const PG8_LAS bf16x8*)(lds + PG8_SA(b, h) + aoff + m * 2048 + k * 1024); } while (0)
; #define PG8_MMA(ai, bj, At, Bt) do { __builtin_amdgcn_s_setprio(1); _Pragma("unroll") for (int m = 0; m < 4; ++m) _Pragma("unroll") for (int n = 0; n < 2; ++n) _Pragma("unroll") for (int k = 0; k < 2; ++k) \
;         acc[ai][bj][m][n] = __builtin_amdgcn_mfma_f32_16x16x32_bf16(Bt[n][k], At[m][k], acc[ai][bj][m][n], 0, 0, 0); __builtin_amdgcn_s_setprio(0); } while (0)
; #define PG8_WAIT_V(n) asm volatile("s_waitcnt vmcnt(" #n ")" ::: "memory")
; #define PG8_WAIT_L(n) asm volatile("s_waitcnt lgkmcnt(" #n ")" ::: "memory")
; #define PG8_BAR __builtin_amdgcn_s_barrier()
; #define PG8_SCHED __builtin_amdgcn_sched_barrier(0)
; template <class Epi, class Sched, bool ALIGN_EPI = false, bool SP2 = false>
; __device__ __forceinline__ void gemm_phase(PG8_LAS unsigned char* lds, const Gemm g, const Sched& S, const Epi& E, const int tid) {
;     ...
;             PG8_LDA(At, 1, 1); PG8_STAGE(PG8_SB(1, 0), b3, voffB); PG8_STAGE(PG8_SB(1, 1), b3 + hstep, voffB); PG8_STAGE(PG8_SA(1, 0), a3, voffA);
;             PG8_WAIT_V(8); PG8_WAIT_L(0); PG8_BAR; PG8_MMA(1, 0, At, B0); PG8_MMA(1, 1, At, B1); PG8_BAR; PG8_SCHED;
;     ...
;         if constexpr (ALIGN_EPI) { if (wr == 0) PG8_BAR; }
	s_add_i32 s26, s26, s20
	v_lshl_add_u64 v[148:149], v[148:149], 0, s[16:17]
	s_mov_b32 m0, s26
	ds_read_b128 v[202:205], v167 offset:49152
	ds_read_b128 v[206:209], v167 offset:50176
	ds_read_b128 v[210:213], v167 offset:51200
	ds_read_b128 v[218:221], v167 offset:52224
	ds_read_b128 v[222:225], v167 offset:53248
	ds_read_b128 v[226:229], v167 offset:54272
	ds_read_b128 v[230:233], v167 offset:55296
	ds_read_b128 v[234:237], v167 offset:56320
	global_load_lds_dwordx4 v[148:149], off
	s_add_i32 m0, s26, 0x2000
	s_add_u32 s34, s46, 0x40080
	v_lshl_add_u64 v[148:149], v[160:161], 0, s[16:17]
	s_addc_u32 s35, s47, 0
	s_add_i32 s26, s27, s20
	global_load_lds_dwordx4 v[148:149], off
	v_lshl_add_u64 v[148:149], s[34:35], 0, v[134:135]
	s_mov_b32 m0, s26
	s_nop 0
	global_load_lds_dwordx4 v[148:149], off
	v_lshl_add_u64 v[148:149], s[34:35], 0, v[138:139]
	s_add_i32 m0, s26, 0x2000
	s_nop 0
	global_load_lds_dwordx4 v[148:149], off
	v_lshl_add_u64 v[148:149], v[214:215], 0, s[16:17]
	s_mov_b32 m0, s54
	s_nop 0
	global_load_lds_dwordx4 v[148:149], off
	v_lshl_add_u64 v[148:149], v[238:239], 0, s[16:17]
	s_mov_b32 m0, s55
	s_nop 0
	global_load_lds_dwordx4 v[148:149], off
	s_waitcnt vmcnt(8)
	s_waitcnt lgkmcnt(0)
	s_barrier
	s_waitcnt lgkmcnt(0)
	v_mfma_f32_16x16x32_bf16 v[66:69], v[144:147], v[202:205], v[66:69]
	v_mfma_f32_16x16x32_bf16 v[62:65], v[178:181], v[202:205], v[62:65]
	v_mfma_f32_16x16x32_bf16 v[50:53], v[144:147], v[210:213], v[50:53]
	v_mfma_f32_16x16x32_bf16 v[46:49], v[178:181], v[210:213], v[46:49]
	v_mfma_f32_16x16x32_bf16 v[34:37], v[144:147], v[222:225], v[34:37]
	v_mfma_f32_16x16x32_bf16 v[30:33], v[178:181], v[222:225], v[30:33]
	v_mfma_f32_16x16x32_bf16 v[18:21], v[144:147], v[230:233], v[18:21]
	v_mfma_f32_16x16x32_bf16 v[14:17], v[178:181], v[230:233], v[14:17]
	v_mfma_f32_16x16x32_bf16 v[66:69], v[174:177], v[206:209], v[66:69]
	v_mfma_f32_16x16x32_bf16 v[62:65], v[182:185], v[206:209], v[62:65]
	v_mfma_f32_16x16x32_bf16 v[50:53], v[174:177], v[218:221], v[50:53]
	v_mfma_f32_16x16x32_bf16 v[46:49], v[182:185], v[218:221], v[46:49]
	v_mfma_f32_16x16x32_bf16 v[34:37], v[174:177], v[226:229], v[34:37]
	v_mfma_f32_16x16x32_bf16 v[30:33], v[182:185], v[226:229], v[30:33]
	v_mfma_f32_16x16x32_bf16 v[18:21], v[174:177], v[234:237], v[18:21]
	v_mfma_f32_16x16x32_bf16 v[14:17], v[182:185], v[234:237], v[14:17]
	v_mfma_f32_16x16x32_bf16 v[58:61], v[186:189], v[202:205], v[58:61]
	v_mfma_f32_16x16x32_bf16 v[54:57], v[194:197], v[202:205], v[54:57]
	v_mfma_f32_16x16x32_bf16 v[42:45], v[186:189], v[210:213], v[42:45]
	v_mfma_f32_16x16x32_bf16 v[38:41], v[194:197], v[210:213], v[38:41]
	v_mfma_f32_16x16x32_bf16 v[26:29], v[186:189], v[222:225], v[26:29]
	v_mfma_f32_16x16x32_bf16 v[22:25], v[194:197], v[222:225], v[22:25]
	v_mfma_f32_16x16x32_bf16 v[10:13], v[186:189], v[230:233], v[10:13]
	v_mfma_f32_16x16x32_bf16 v[6:9], v[194:197], v[230:233], v[6:9]
	v_mfma_f32_16x16x32_bf16 v[58:61], v[190:193], v[206:209], v[58:61]
	v_mfma_f32_16x16x32_bf16 v[54:57], v[198:201], v[206:209], v[54:57]
	v_mfma_f32_16x16x32_bf16 v[42:45], v[190:193], v[218:221], v[42:45]
	v_mfma_f32_16x16x32_bf16 v[38:41], v[198:201], v[218:221], v[38:41]
	v_mfma_f32_16x16x32_bf16 v[26:29], v[190:193], v[226:229], v[26:29]
	v_mfma_f32_16x16x32_bf16 v[22:25], v[198:201], v[226:229], v[22:25]
	v_mfma_f32_16x16x32_bf16 v[10:13], v[190:193], v[234:237], v[10:13]
	v_mfma_f32_16x16x32_bf16 v[6:9], v[198:201], v[234:237], v[6:9]
	s_barrier
	s_add_i32 s33, s33, 2
	s_add_u32 s44, s44, 0x100
	s_addc_u32 s45, s45, 0
	s_add_u32 s18, s18, 0x100
	s_addc_u32 s19, s19, 0
	s_cmp_gt_u32 s33, 13
	s_cbranch_scc0 .LBB0_496
	s_and_b64 vcc, exec, s[10:11]
	s_cbranch_vccz .LBB0_499
	s_barrier

; #define PG8_WAIT_V(n) asm volatile("s_waitcnt vmcnt(" #n ")" ::: "memory")
; #define PG8_BAR __builtin_amdgcn_s_barrier()
; template <class Epi, class Sched, bool ALIGN_EPI = false, bool SP2 = false>
; __device__ __forceinline__ void gemm_phase(PG8_LAS unsigned char* lds, const Gemm g, const Sched& S, const Epi& E, const int tid) {
;     ...
;     PG8_WAIT_V(0);
;     if constexpr (!ALIGN_EPI) { if (wr == 0) PG8_BAR; }
;     PG8_BAR;
; DI void xcd_barrier(const XcdBarrier& b) {
;     asm volatile("s_waitcnt vmcnt(0)" ::: "memory");
;     __syncthreads();
;     if (threadIdx.x == 0) {
;         unsigned* bar = b.bar;
;         __builtin_amdgcn_s_waitcnt(0);
;         unsigned nloc = b.st[0], nx = b.st[1];
;         if (nloc == 0u) { xcd_barrier_complete(bar, b.x, nloc, nx); b.st[0] = nloc; b.st[1] = nx; }
.LBB0_567:
	s_setprio 0
	s_waitcnt vmcnt(0)
	s_waitcnt lgkmcnt(0)
	s_barrier
	s_and_saveexec_b64 s[2:3], s[90:91]
	v_readlane_b32 s34, v254, 34
	v_readlane_b32 s35, v254, 35
	v_readlane_b32 s57, v254, 58
	v_readlane_b32 s58, v254, 59
	v_readlane_b32 s59, v254, 60
	v_readlane_b32 s62, v254, 62
	v_readlane_b32 s63, v254, 63
	s_cbranch_execz .LBB0_619
	v_readlane_b32 s0, v253, 60
	s_waitcnt vmcnt(0) expcnt(0) lgkmcnt(0)
	s_nop 0
	v_mov_b32_e32 v1, s0
	ds_read_b32 v3, v1
	v_readlane_b32 s0, v253, 61
	s_waitcnt lgkmcnt(0)
	v_cmp_ne_u32_e32 vcc, 0, v3
	v_mov_b32_e32 v1, s0
	ds_read_b32 v2, v1
	s_cbranch_vccnz .LBB0_583
	s_mov_b32 s0, 1
	s_branch .LBB0_571

; #define PG8_LAS __attribute__((address_space(3)))
; #define LAUNDER() asm volatile("" : "+v"(tid), "+s"(bid), "+s"(nb))
; DI void xcd_barrier(const XcdBarrier& b) {
;     ...
;     __syncthreads();
; __global__ void __launch_bounds__(NT, 2) mega_fwd(Ctx c) {
;     ...
;             for (int rep = 0; rep < REP_GUP; ++rep) { LAUNDER(); pg8::EpiUp E{ACT, c.conv_w + (size_t)l * 3 * DFF, c.conv_b + (size_t)l * DFF, g < 2 ? 16384 : 4096, MG, DFF, (PG8_LAS float*)(lds + 131072), SSQ2};
;                 run_gemm(lds, H2 - DM, (const bf16*)(ws + WS_WUP + l * SZ_WUP), NUP, DM, E, bid, nb, tid, 254, 65 * 256); }
.LBB0_619:
	s_or_b64 exec, exec, s[2:3]
	s_waitcnt lgkmcnt(0)
	s_barrier
	v_readfirstlane_b32 s98, v158
	s_nop 3
	s_lshr_b32 s98, s98, 6
	s_cmp_ge_u32 s98, 4
	s_cbranch_scc0 .Lprio_skip_2
	s_setprio 1

; #define PG8_STAGE(bufoff, gbase, voff) do { _Pragma("unroll") for (int _i = 0; _i < 2; ++_i) \
;         __builtin_amdgcn_global_load_lds((const unsigned*)((const char*)(gbase) + (voff)[_i]), (PG8_LAS unsigned*)(lds + (bufoff) + ldsw + _i * 8192), 16, 0, 0); } while (0)
; #define PG8_LDA(dst, b, h) do { _Pragma("unroll") for (int m = 0; m < 4; ++m) _Pragma("unroll") for (int k = 0; k < 2; ++k) dst[m][k] = *(const PG8_LAS bf16x8*)(lds + PG8_SA(b, h) + aoff + m * 2048 + k * 1024); } while (0)
; #define PG8_LDB(dst, b, h) do { _Pragma("unroll") for (int n = 0; n < 2; ++n) _Pragma("unroll") for (int k = 0; k < 2; ++k) dst[n][k] = *(const PG8_LAS bf16x8*)(lds + PG8_SB(b, h) + boff + n * 2048 + k * 1024); } while (0)
; #define PG8_MMA(ai, bj, At, Bt) do { __builtin_amdgcn_s_setprio(1); _Pragma("unroll") for (int m = 0; m < 4; ++m) _Pragma("unroll") for (int n = 0; n < 2; ++n) _Pragma("unroll") for (int k = 0; k < 2; ++k) \
;         acc[ai][bj][m][n] = __builtin_amdgcn_mfma_f32_16x16x32_bf16(Bt[n][k], At[m][k], acc[ai][bj][m][n], 0, 0, 0); __builtin_amdgcn_s_setprio(0); } while (0)
; #define PG8_WAIT_V(n) asm volatile("s_waitcnt vmcnt(" #n ")" ::: "memory")
; #define PG8_WAIT_L(n) asm volatile("s_waitcnt lgkmcnt(" #n ")" ::: "memory")
; #define PG8_BAR __builtin_amdgcn_s_barrier()
; #define PG8_SCHED __builtin_amdgcn_sched_barrier(0)
; template <class Epi, class Sched, bool ALIGN_EPI = false, bool SP2 = false>
; __device__ __forceinline__ void gemm_phase(PG8_LAS unsigned char* lds, const Gemm g, const Sched& S, const Epi& E, const int tid) {
;     ...
;             PG8_LDB(B0, 0, 0); PG8_LDB(B1, 0, 1); PG8_SCHED; PG8_LDA(At, 0, 0); PG8_STAGE(PG8_SA(1, 1), a1 + hstep, voffA);
;             PG8_WAIT_V(8); PG8_WAIT_L(0); PG8_BAR; PG8_MMA(0, 0, At, B0); PG8_MMA(0, 1, At, B1); PG8_BAR; PG8_SCHED;
;             PG8_LDA(At, 0, 1); PG8_STAGE(PG8_SB(0, 0), b2, voffB); PG8_STAGE(PG8_SB(0, 1), b2 + hstep, voffB); PG8_STAGE(PG8_SA(0, 0), a2, voffA);
;             PG8_WAIT_V(8); PG8_WAIT_L(0); PG8_BAR; PG8_MMA(1, 0, At, B0); PG8_MMA(1, 1, At, B1); PG8_BAR; PG8_SCHED;
.LBB0_641:
	s_add_u32 s26, s44, 0xfffc0080
	s_addc_u32 s27, s45, -1
	s_add_i32 s35, 0, 0x10000
	s_cmp_eq_u32 s34, 12
	s_cselect_b32 s63, s57, s27
	s_cselect_b32 s62, s56, s26
	s_cselect_b32 s61, s1, s33
	s_cselect_b32 s60, s18, s19
	s_add_i32 s26, 0, 0x14000
	v_add_u32_e32 v58, s35, v159
	v_add_u32_e32 v160, s26, v159
	ds_read_b128 v[46:49], v58
	ds_read_b128 v[50:53], v58 offset:1024
	ds_read_b128 v[54:57], v58 offset:2048
	ds_read_b128 v[58:61], v58 offset:3072
	ds_read_b128 v[70:73], v160
	ds_read_b128 v[74:77], v160 offset:1024
	ds_read_b128 v[174:177], v160 offset:2048
	ds_read_b128 v[178:181], v160 offset:3072
	v_lshl_add_u64 v[160:161], s[44:45], 0, v[170:171]
	s_add_i32 m0, s68, 0xc000
	ds_read_b128 v[182:185], v243
	ds_read_b128 v[186:189], v243 offset:1024
	ds_read_b128 v[190:193], v243 offset:2048
	ds_read_b128 v[194:197], v243 offset:3072
	ds_read_b128 v[198:201], v243 offset:4096
	ds_read_b128 v[202:205], v243 offset:5120
	ds_read_b128 v[206:209], v243 offset:6144
	ds_read_b128 v[210:213], v243 offset:7168
	global_load_lds_dwordx4 v[160:161], off
	v_lshl_add_u64 v[160:161], s[44:45], 0, v[172:173]
	s_add_i32 m0, s68, 0xe000
	s_nop 0
	global_load_lds_dwordx4 v[160:161], off
	s_waitcnt vmcnt(8)
	s_waitcnt lgkmcnt(0)
	s_barrier
	s_waitcnt lgkmcnt(0)
	v_mfma_f32_16x16x32_bf16 v[62:65], v[46:49], v[182:185], v[62:65]
	v_mfma_f32_16x16x32_bf16 v[146:149], v[54:57], v[182:185], v[146:149]
	v_mfma_f32_16x16x32_bf16 v[66:69], v[46:49], v[190:193], v[66:69]
	v_mfma_f32_16x16x32_bf16 v[154:157], v[54:57], v[190:193], v[154:157]
	v_mfma_f32_16x16x32_bf16 v[138:141], v[46:49], v[198:201], v[138:141]
	v_mfma_f32_16x16x32_bf16 v[134:137], v[54:57], v[198:201], v[134:137]
	v_mfma_f32_16x16x32_bf16 v[122:125], v[46:49], v[206:209], v[122:125]
	v_mfma_f32_16x16x32_bf16 v[118:121], v[54:57], v[206:209], v[118:121]
	v_mfma_f32_16x16x32_bf16 v[62:65], v[50:53], v[186:189], v[62:65]
	v_mfma_f32_16x16x32_bf16 v[146:149], v[58:61], v[186:189], v[146:149]
	v_mfma_f32_16x16x32_bf16 v[66:69], v[50:53], v[194:197], v[66:69]
	v_mfma_f32_16x16x32_bf16 v[154:157], v[58:61], v[194:197], v[154:157]
	v_mfma_f32_16x16x32_bf16 v[138:141], v[50:53], v[202:205], v[138:141]
	v_mfma_f32_16x16x32_bf16 v[134:137], v[58:61], v[202:205], v[134:137]
	v_mfma_f32_16x16x32_bf16 v[122:125], v[50:53], v[210:213], v[122:125]
	v_mfma_f32_16x16x32_bf16 v[118:121], v[58:61], v[210:213], v[118:121]
	v_mfma_f32_16x16x32_bf16 v[150:153], v[70:73], v[182:185], v[150:153]
	v_mfma_f32_16x16x32_bf16 v[142:145], v[174:177], v[182:185], v[142:145]
	v_mfma_f32_16x16x32_bf16 v[130:133], v[70:73], v[190:193], v[130:133]
	v_mfma_f32_16x16x32_bf16 v[126:129], v[174:177], v[190:193], v[126:129]
	v_mfma_f32_16x16x32_bf16 v[114:117], v[70:73], v[198:201], v[114:117]
	v_mfma_f32_16x16x32_bf16 v[110:113], v[174:177], v[198:201], v[110:113]
	v_mfma_f32_16x16x32_bf16 v[106:109], v[70:73], v[206:209], v[106:109]
	v_mfma_f32_16x16x32_bf16 v[102:105], v[174:177], v[206:209], v[102:105]
	v_mfma_f32_16x16x32_bf16 v[150:153], v[74:77], v[186:189], v[150:153]
	v_mfma_f32_16x16x32_bf16 v[142:145], v[178:181], v[186:189], v[142:145]
	v_mfma_f32_16x16x32_bf16 v[130:133], v[74:77], v[194:197], v[130:133]
	v_mfma_f32_16x16x32_bf16 v[126:129], v[178:181], v[194:197], v[126:129]
	v_mfma_f32_16x16x32_bf16 v[114:117], v[74:77], v[202:205], v[114:117]
	v_mfma_f32_16x16x32_bf16 v[110:113], v[178:181], v[202:205], v[110:113]
	v_mfma_f32_16x16x32_bf16 v[106:109], v[74:77], v[210:213], v[106:109]
	v_mfma_f32_16x16x32_bf16 v[102:105], v[178:181], v[210:213], v[102:105]
	s_barrier
	s_add_i32 s27, s35, s67
	v_lshl_add_u64 v[160:161], s[60:61], 0, v[164:165]
	s_mov_b32 m0, s27
	ds_read_b128 v[182:185], v243 offset:16384
	ds_read_b128 v[186:189], v243 offset:17408
	ds_read_b128 v[190:193], v243 offset:18432
	ds_read_b128 v[194:197], v243 offset:19456
	ds_read_b128 v[198:201], v243 offset:20480
	ds_read_b128 v[202:205], v243 offset:21504
	ds_read_b128 v[206:209], v243 offset:22528
	ds_read_b128 v[210:213], v243 offset:23552
	global_load_lds_dwordx4 v[160:161], off
	s_add_i32 m0, s27, 0x2000
	s_add_u32 s64, s60, 0x40000
	v_lshl_add_u64 v[214:215], s[60:61], 0, v[168:169]
	s_addc_u32 s65, s61, 0
	s_add_i32 s26, s26, s67
	global_load_lds_dwordx4 v[214:215], off
	v_lshl_add_u64 v[244:245], s[64:65], 0, v[164:165]
	s_mov_b32 m0, s26
	v_lshl_add_u64 v[248:249], s[62:63], 0, v[2:3]
	global_load_lds_dwordx4 v[244:245], off
	v_lshl_add_u64 v[244:245], s[64:65], 0, v[168:169]
	s_add_i32 m0, s26, 0x2000
	v_lshl_add_u64 v[250:251], s[62:63], 0, v[166:167]
	global_load_lds_dwordx4 v[244:245], off
	s_mov_b32 m0, s68
	s_nop 0
	global_load_lds_dwordx4 v[248:249], off
	s_mov_b32 m0, s69
	s_nop 0
	global_load_lds_dwordx4 v[250:251], off
	s_waitcnt vmcnt(8)
	s_waitcnt lgkmcnt(0)
	s_barrier
; #define PG8_STAGE(bufoff, gbase, voff) do { _Pragma("unroll") for (int _i = 0; _i < 2; ++_i) \
;         __builtin_amdgcn_global_load_lds((const unsigned*)((const char*)(gbase) + (voff)[_i]), (PG8_LAS unsigned*)(lds + (bufoff) + ldsw + _i * 8192), 16, 0, 0); } while (0)
; #define PG8_LDA(dst, b, h) do { _Pragma("unroll") for (int m = 0; m < 4; ++m) _Pragma("unroll") for (int k = 0; k < 2; ++k) dst[m][k] = *(const PG8_LAS bf16x8*)(lds + PG8_SA(b, h) + aoff + m * 2048 + k * 1024); } while (0)
; #define PG8_LDB(dst, b, h) do { _Pragma("unroll") for (int n = 0; n < 2; ++n) _Pragma("unroll") for (int k = 0; k < 2; ++k) dst[n][k] = *(const PG8_LAS bf16x8*)(lds + PG8_SB(b, h) + boff + n * 2048 + k * 1024); } while (0)
; #define PG8_MMA(ai, bj, At, Bt) do { __builtin_amdgcn_s_setprio(1); _Pragma("unroll") for (int m = 0; m < 4; ++m) _Pragma("unroll") for (int n = 0; n < 2; ++n) _Pragma("unroll") for (int k = 0; k < 2; ++k) \
;         acc[ai][bj][m][n] = __builtin_amdgcn_mfma_f32_16x16x32_bf16(Bt[n][k], At[m][k], acc[ai][bj][m][n], 0, 0, 0); __builtin_amdgcn_s_setprio(0); } while (0)
; #define PG8_WAIT_V(n) asm volatile("s_waitcnt vmcnt(" #n ")" ::: "memory")
; #define PG8_WAIT_L(n) asm volatile("s_waitcnt lgkmcnt(" #n ")" ::: "memory")
; #define PG8_BAR __builtin_amdgcn_s_barrier()
; #define PG8_SCHED __builtin_amdgcn_sched_barrier(0)
; template <class Epi, class Sched, bool ALIGN_EPI = false, bool SP2 = false>
; __device__ __forceinline__ void gemm_phase(PG8_LAS unsigned char* lds, const Gemm g, const Sched& S, const Epi& E, const int tid) {
;     ...
;             PG8_WAIT_V(8); PG8_WAIT_L(0); PG8_BAR; PG8_MMA(1, 0, At, B0); PG8_MMA(1, 1, At, B1); PG8_BAR; PG8_SCHED;
;             PG8_LDB(B0, 1, 0); PG8_LDB(B1, 1, 1); PG8_SCHED; PG8_LDA(At, 1, 0); PG8_STAGE(PG8_SA(0, 1), a2 + hstep, voffA);
;             PG8_WAIT_V(8); PG8_WAIT_L(0); PG8_BAR; PG8_MMA(0, 0, At, B0); PG8_MMA(0, 1, At, B1); PG8_BAR; PG8_SCHED;
	s_waitcnt lgkmcnt(0)
	v_mfma_f32_16x16x32_bf16 v[90:93], v[46:49], v[182:185], v[90:93]
	v_mfma_f32_16x16x32_bf16 v[86:89], v[54:57], v[182:185], v[86:89]
	v_mfma_f32_16x16x32_bf16 v[98:101], v[46:49], v[190:193], v[98:101]
	v_mfma_f32_16x16x32_bf16 v[94:97], v[54:57], v[190:193], v[94:97]
	v_mfma_f32_16x16x32_bf16 v[42:45], v[46:49], v[198:201], v[42:45]
	v_mfma_f32_16x16x32_bf16 v[38:41], v[54:57], v[198:201], v[38:41]
	v_mfma_f32_16x16x32_bf16 v[26:29], v[46:49], v[206:209], v[26:29]
	v_mfma_f32_16x16x32_bf16 v[22:25], v[54:57], v[206:209], v[22:25]
	v_mfma_f32_16x16x32_bf16 v[90:93], v[50:53], v[186:189], v[90:93]
	v_mfma_f32_16x16x32_bf16 v[86:89], v[58:61], v[186:189], v[86:89]
	v_mfma_f32_16x16x32_bf16 v[98:101], v[50:53], v[194:197], v[98:101]
	v_mfma_f32_16x16x32_bf16 v[94:97], v[58:61], v[194:197], v[94:97]
	v_mfma_f32_16x16x32_bf16 v[42:45], v[50:53], v[202:205], v[42:45]
	v_mfma_f32_16x16x32_bf16 v[38:41], v[58:61], v[202:205], v[38:41]
	v_mfma_f32_16x16x32_bf16 v[26:29], v[50:53], v[210:213], v[26:29]
	v_mfma_f32_16x16x32_bf16 v[22:25], v[58:61], v[210:213], v[22:25]
	v_mfma_f32_16x16x32_bf16 v[34:37], v[70:73], v[190:193], v[34:37]
	v_mfma_f32_16x16x32_bf16 v[30:33], v[174:177], v[190:193], v[30:33]
	v_mfma_f32_16x16x32_bf16 v[18:21], v[70:73], v[198:201], v[18:21]
	v_mfma_f32_16x16x32_bf16 v[14:17], v[174:177], v[198:201], v[14:17]
	v_mfma_f32_16x16x32_bf16 v[10:13], v[70:73], v[206:209], v[10:13]
	v_mfma_f32_16x16x32_bf16 v[6:9], v[174:177], v[206:209], v[6:9]
	v_mfma_f32_16x16x32_bf16 v[46:49], v[70:73], v[182:185], v[82:85]
	v_mfma_f32_16x16x32_bf16 v[50:53], v[174:177], v[182:185], v[78:81]
	v_mfma_f32_16x16x32_bf16 v[34:37], v[74:77], v[194:197], v[34:37]
	v_mfma_f32_16x16x32_bf16 v[30:33], v[178:181], v[194:197], v[30:33]
	v_mfma_f32_16x16x32_bf16 v[18:21], v[74:77], v[202:205], v[18:21]
	v_mfma_f32_16x16x32_bf16 v[14:17], v[178:181], v[202:205], v[14:17]
	v_mfma_f32_16x16x32_bf16 v[10:13], v[74:77], v[210:213], v[10:13]
	v_mfma_f32_16x16x32_bf16 v[6:9], v[178:181], v[210:213], v[6:9]
	v_mfma_f32_16x16x32_bf16 v[46:49], v[74:77], v[186:189], v[46:49]
	v_mfma_f32_16x16x32_bf16 v[50:53], v[178:181], v[186:189], v[50:53]
	s_barrier
	s_add_i32 s26, 0, 0x18000
	s_add_i32 s27, 0, 0x1c000
	v_add_u32_e32 v74, s26, v159
	v_add_u32_e32 v78, s27, v159
	ds_read_b128 v[54:57], v74
	ds_read_b128 v[58:61], v74 offset:1024
	ds_read_b128 v[70:73], v74 offset:2048
	ds_read_b128 v[74:77], v74 offset:3072
	ds_read_b128 v[174:177], v78
	ds_read_b128 v[178:181], v78 offset:1024
	ds_read_b128 v[182:185], v78 offset:2048
	ds_read_b128 v[186:189], v78 offset:3072
	s_add_u32 s62, s62, 0x40000
	s_addc_u32 s63, s63, 0
	s_mov_b32 m0, s70
	v_lshl_add_u64 v[244:245], s[62:63], 0, v[2:3]
	ds_read_b128 v[78:81], v243 offset:32768
	ds_read_b128 v[82:85], v243 offset:33792
	ds_read_b128 v[190:193], v243 offset:34816
	ds_read_b128 v[194:197], v243 offset:35840
	ds_read_b128 v[198:201], v243 offset:36864
	ds_read_b128 v[202:205], v243 offset:37888
	ds_read_b128 v[206:209], v243 offset:38912
	ds_read_b128 v[210:213], v243 offset:39936
	global_load_lds_dwordx4 v[244:245], off
	v_lshl_add_u64 v[244:245], s[62:63], 0, v[166:167]
	s_mov_b32 m0, s71
	s_nop 0
	global_load_lds_dwordx4 v[244:245], off
	s_waitcnt vmcnt(8)
	s_waitcnt lgkmcnt(0)
	s_barrier
	s_waitcnt lgkmcnt(0)
	v_mfma_f32_16x16x32_bf16 v[62:65], v[54:57], v[78:81], v[62:65]
	v_mfma_f32_16x16x32_bf16 v[146:149], v[70:73], v[78:81], v[146:149]
	v_mfma_f32_16x16x32_bf16 v[66:69], v[54:57], v[190:193], v[66:69]
	v_mfma_f32_16x16x32_bf16 v[154:157], v[70:73], v[190:193], v[154:157]
	v_mfma_f32_16x16x32_bf16 v[138:141], v[54:57], v[198:201], v[138:141]
	v_mfma_f32_16x16x32_bf16 v[134:137], v[70:73], v[198:201], v[134:137]
	v_mfma_f32_16x16x32_bf16 v[122:125], v[54:57], v[206:209], v[122:125]
	v_mfma_f32_16x16x32_bf16 v[118:121], v[70:73], v[206:209], v[118:121]
	v_mfma_f32_16x16x32_bf16 v[62:65], v[58:61], v[82:85], v[62:65]
	v_mfma_f32_16x16x32_bf16 v[146:149], v[74:77], v[82:85], v[146:149]
	v_mfma_f32_16x16x32_bf16 v[66:69], v[58:61], v[194:197], v[66:69]
	v_mfma_f32_16x16x32_bf16 v[154:157], v[74:77], v[194:197], v[154:157]
	v_mfma_f32_16x16x32_bf16 v[138:141], v[58:61], v[202:205], v[138:141]
	v_mfma_f32_16x16x32_bf16 v[134:137], v[74:77], v[202:205], v[134:137]
	v_mfma_f32_16x16x32_bf16 v[122:125], v[58:61], v[210:213], v[122:125]
	v_mfma_f32_16x16x32_bf16 v[118:121], v[74:77], v[210:213], v[118:121]
	v_mfma_f32_16x16x32_bf16 v[150:153], v[174:177], v[78:81], v[150:153]
	v_mfma_f32_16x16x32_bf16 v[78:81], v[182:185], v[78:81], v[142:145]
	v_mfma_f32_16x16x32_bf16 v[142:145], v[186:189], v[82:85], v[78:81]
	v_mfma_f32_16x16x32_bf16 v[78:81], v[174:177], v[190:193], v[130:133]
	v_mfma_f32_16x16x32_bf16 v[130:133], v[178:181], v[194:197], v[78:81]
	v_mfma_f32_16x16x32_bf16 v[78:81], v[182:185], v[190:193], v[126:129]
	v_mfma_f32_16x16x32_bf16 v[126:129], v[186:189], v[194:197], v[78:81]
	v_mfma_f32_16x16x32_bf16 v[78:81], v[174:177], v[198:201], v[114:117]
	v_mfma_f32_16x16x32_bf16 v[114:117], v[178:181], v[202:205], v[78:81]
	v_mfma_f32_16x16x32_bf16 v[78:81], v[182:185], v[198:201], v[110:113]
	v_mfma_f32_16x16x32_bf16 v[110:113], v[186:189], v[202:205], v[78:81]
	v_mfma_f32_16x16x32_bf16 v[78:81], v[174:177], v[206:209], v[106:109]
	v_mfma_f32_16x16x32_bf16 v[106:109], v[178:181], v[210:213], v[78:81]
	v_mfma_f32_16x16x32_bf16 v[78:81], v[182:185], v[206:209], v[102:105]
	v_mfma_f32_16x16x32_bf16 v[150:153], v[178:181], v[82:85], v[150:153]
	v_mfma_f32_16x16x32_bf16 v[102:105], v[186:189], v[210:213], v[78:81]
	s_barrier
; #define PG8_STAGE(bufoff, gbase, voff) do { _Pragma("unroll") for (int _i = 0; _i < 2; ++_i) \
;         __builtin_amdgcn_global_load_lds((const unsigned*)((const char*)(gbase) + (voff)[_i]), (PG8_LAS unsigned*)(lds + (bufoff) + ldsw + _i * 8192), 16, 0, 0); } while (0)
; #define PG8_LDA(dst, b, h) do { _Pragma("unroll") for (int m = 0; m < 4; ++m) _Pragma("unroll") for (int k = 0; k < 2; ++k) dst[m][k] = *(const PG8_LAS bf16x8*)(lds + PG8_SA(b, h) + aoff + m * 2048 + k * 1024); } while (0)
; #define PG8_MMA(ai, bj, At, Bt) do { __builtin_amdgcn_s_setprio(1); _Pragma("unroll") for (int m = 0; m < 4; ++m) _Pragma("unroll") for (int n = 0; n < 2; ++n) _Pragma("unroll") for (int k = 0; k < 2; ++k) \
;         acc[ai][bj][m][n] = __builtin_amdgcn_mfma_f32_16x16x32_bf16(Bt[n][k], At[m][k], acc[ai][bj][m][n], 0, 0, 0); __builtin_amdgcn_s_setprio(0); } while (0)
; #define PG8_WAIT_V(n) asm volatile("s_waitcnt vmcnt(" #n ")" ::: "memory")
; #define PG8_WAIT_L(n) asm volatile("s_waitcnt lgkmcnt(" #n ")" ::: "memory")
; #define PG8_BAR __builtin_amdgcn_s_barrier()
; #define PG8_SCHED __builtin_amdgcn_sched_barrier(0)
; template <class Epi, class Sched, bool ALIGN_EPI = false, bool SP2 = false>
; __device__ __forceinline__ void gemm_phase(PG8_LAS unsigned char* lds, const Gemm g, const Sched& S, const Epi& E, const int tid) {
;     ...
;             PG8_LDA(At, 1, 1); PG8_STAGE(PG8_SB(1, 0), b3, voffB); PG8_STAGE(PG8_SB(1, 1), b3 + hstep, voffB); PG8_STAGE(PG8_SA(1, 0), a3, voffA);
;             PG8_WAIT_V(8); PG8_WAIT_L(0); PG8_BAR; PG8_MMA(1, 0, At, B0); PG8_MMA(1, 1, At, B1); PG8_BAR; PG8_SCHED;
;     ...
;         if constexpr (ALIGN_EPI) { if (wr == 0) PG8_BAR; }
	s_add_i32 s26, s26, s67
	v_lshl_add_u64 v[82:83], v[160:161], 0, s[16:17]
	s_mov_b32 m0, s26
	s_nop 0
	ds_read_b128 v[78:81], v243 offset:49152
	ds_read_b128 v[190:193], v243 offset:50176
	ds_read_b128 v[194:197], v243 offset:51200
	ds_read_b128 v[198:201], v243 offset:52224
	ds_read_b128 v[202:205], v243 offset:53248
	ds_read_b128 v[206:209], v243 offset:54272
	ds_read_b128 v[210:213], v243 offset:55296
	ds_read_b128 v[244:247], v243 offset:56320
	global_load_lds_dwordx4 v[82:83], off
	s_add_i32 m0, s26, 0x2000
	s_add_u32 s60, s60, 0x40080
	v_lshl_add_u64 v[82:83], v[214:215], 0, s[16:17]
	s_addc_u32 s61, s61, 0
	s_add_i32 s26, s27, s67
	global_load_lds_dwordx4 v[82:83], off
	v_lshl_add_u64 v[82:83], s[60:61], 0, v[164:165]
	s_mov_b32 m0, s26
	s_nop 0
	global_load_lds_dwordx4 v[82:83], off
	v_lshl_add_u64 v[82:83], s[60:61], 0, v[168:169]
	s_add_i32 m0, s26, 0x2000
	s_nop 0
	global_load_lds_dwordx4 v[82:83], off
	v_lshl_add_u64 v[82:83], v[248:249], 0, s[16:17]
	s_mov_b32 m0, s72
	s_nop 0
	global_load_lds_dwordx4 v[82:83], off
	v_lshl_add_u64 v[82:83], v[250:251], 0, s[16:17]
	s_mov_b32 m0, s73
	s_nop 0
	global_load_lds_dwordx4 v[82:83], off
	s_waitcnt vmcnt(8)
	s_waitcnt lgkmcnt(0)
	s_barrier
	s_waitcnt lgkmcnt(0)
	v_mfma_f32_16x16x32_bf16 v[82:85], v[54:57], v[78:81], v[90:93]
	v_mfma_f32_16x16x32_bf16 v[90:93], v[58:61], v[190:193], v[82:85]
	v_mfma_f32_16x16x32_bf16 v[82:85], v[70:73], v[78:81], v[86:89]
	v_mfma_f32_16x16x32_bf16 v[86:89], v[74:77], v[190:193], v[82:85]
	v_mfma_f32_16x16x32_bf16 v[82:85], v[54:57], v[194:197], v[98:101]
	v_mfma_f32_16x16x32_bf16 v[98:101], v[58:61], v[198:201], v[82:85]
	v_mfma_f32_16x16x32_bf16 v[82:85], v[70:73], v[194:197], v[94:97]
	v_mfma_f32_16x16x32_bf16 v[42:45], v[54:57], v[202:205], v[42:45]
	v_mfma_f32_16x16x32_bf16 v[38:41], v[70:73], v[202:205], v[38:41]
	v_mfma_f32_16x16x32_bf16 v[26:29], v[54:57], v[210:213], v[26:29]
	v_mfma_f32_16x16x32_bf16 v[22:25], v[70:73], v[210:213], v[22:25]
	v_mfma_f32_16x16x32_bf16 v[94:97], v[74:77], v[198:201], v[82:85]
	v_mfma_f32_16x16x32_bf16 v[42:45], v[58:61], v[206:209], v[42:45]
	v_mfma_f32_16x16x32_bf16 v[38:41], v[74:77], v[206:209], v[38:41]
	v_mfma_f32_16x16x32_bf16 v[26:29], v[58:61], v[244:247], v[26:29]
	v_mfma_f32_16x16x32_bf16 v[22:25], v[74:77], v[244:247], v[22:25]
	v_mfma_f32_16x16x32_bf16 v[46:49], v[174:177], v[78:81], v[46:49]
	v_mfma_f32_16x16x32_bf16 v[82:85], v[178:181], v[190:193], v[46:49]
	v_mfma_f32_16x16x32_bf16 v[46:49], v[182:185], v[78:81], v[50:53]
	v_mfma_f32_16x16x32_bf16 v[34:37], v[174:177], v[194:197], v[34:37]
	v_mfma_f32_16x16x32_bf16 v[30:33], v[182:185], v[194:197], v[30:33]
	v_mfma_f32_16x16x32_bf16 v[18:21], v[174:177], v[202:205], v[18:21]
	v_mfma_f32_16x16x32_bf16 v[14:17], v[182:185], v[202:205], v[14:17]
	v_mfma_f32_16x16x32_bf16 v[10:13], v[174:177], v[210:213], v[10:13]
	v_mfma_f32_16x16x32_bf16 v[6:9], v[182:185], v[210:213], v[6:9]
	v_mfma_f32_16x16x32_bf16 v[78:81], v[186:189], v[190:193], v[46:49]
	v_mfma_f32_16x16x32_bf16 v[34:37], v[178:181], v[198:201], v[34:37]
	v_mfma_f32_16x16x32_bf16 v[30:33], v[186:189], v[198:201], v[30:33]
	v_mfma_f32_16x16x32_bf16 v[18:21], v[178:181], v[206:209], v[18:21]
	v_mfma_f32_16x16x32_bf16 v[14:17], v[186:189], v[206:209], v[14:17]
	v_mfma_f32_16x16x32_bf16 v[10:13], v[178:181], v[244:247], v[10:13]
	v_mfma_f32_16x16x32_bf16 v[6:9], v[186:189], v[244:247], v[6:9]
	s_barrier
	s_add_i32 s34, s34, 2
	s_add_u32 s44, s44, 0x100
	s_addc_u32 s45, s45, 0
	s_add_u32 s19, s19, 0x100
	s_addc_u32 s33, s33, 0
	s_cmp_gt_u32 s34, 13
	s_cbranch_scc0 .LBB0_641
	s_and_b64 vcc, exec, s[50:51]
	s_cbranch_vccz .LBB0_644
	s_barrier

; #define PG8_WAIT_V(n) asm volatile("s_waitcnt vmcnt(" #n ")" ::: "memory")
; #define PG8_BAR __builtin_amdgcn_s_barrier()
; template <class Epi, class Sched, bool ALIGN_EPI = false, bool SP2 = false>
; __device__ __forceinline__ void gemm_phase(PG8_LAS unsigned char* lds, const Gemm g, const Sched& S, const Epi& E, const int tid) {
;     ...
;     PG8_WAIT_V(0);
;     if constexpr (!ALIGN_EPI) { if (wr == 0) PG8_BAR; }
;     PG8_BAR;
; DI void xcd_barrier(const XcdBarrier& b) {
;     asm volatile("s_waitcnt vmcnt(0)" ::: "memory");
;     __syncthreads();
;     if (threadIdx.x == 0) {
;         unsigned* bar = b.bar;
;         __builtin_amdgcn_s_waitcnt(0);
;         unsigned nloc = b.st[0], nx = b.st[1];
;         if (nloc == 0u) { xcd_barrier_complete(bar, b.x, nloc, nx); b.st[0] = nloc; b.st[1] = nx; }
.LBB0_685:
	s_setprio 0
	s_waitcnt vmcnt(0)
	s_barrier
	s_and_saveexec_b64 s[0:1], s[90:91]
	v_readlane_b32 s82, v254, 22
	s_xor_b64 s[2:3], exec, s[0:1]
	v_readlane_b32 s83, v254, 23
	s_cbranch_execz .LBB0_738
	v_readlane_b32 s0, v253, 60
	s_waitcnt vmcnt(0) expcnt(0) lgkmcnt(0)
	s_nop 0
	v_mov_b32_e32 v1, s0
	ds_read_b32 v3, v1
	v_readlane_b32 s0, v253, 61
	s_waitcnt lgkmcnt(0)
	v_cmp_ne_u32_e32 vcc, 0, v3
	v_mov_b32_e32 v1, s0
	ds_read_b32 v2, v1
	s_cbranch_vccnz .LBB0_701
	s_mov_b32 s0, 1
	s_branch .LBB0_689

;     __host__ __device__ bool next(int i, Unit& u) const {
;         const long L = (long)i * G + c; if (L >= nwg) return false;
;         int wgid = (int)L; { const int q = nwg / NXCD, r = nwg % NXCD, xcd = wgid % NXCD, off = wgid / NXCD; wgid = (xcd < r ? xcd * (q + 1) : r * (q + 1) + (xcd - r) * q) + off; }
; template <class Epi, class Sched, bool ALIGN_EPI = false, bool SP2 = false>
; __device__ __forceinline__ void gemm_phase(PG8_LAS unsigned char* lds, const Gemm g, const Sched& S, const Epi& E, const int tid) {
;     ...
;     if (!S.next(0, cur)) return;
.Lprio_skip_3:
	s_cbranch_vccz .LBB0_768
	s_cmpk_gt_i32 s86, 0xff
	v_readfirstlane_b32 s4, v158
	s_cbranch_scc1 .LBB0_767
	s_ashr_i32 s20, s86, 31
	s_lshr_b32 s0, s20, 29
	s_add_i32 s1, s86, s0
	s_and_b32 s0, s1, -8
	s_sub_i32 s5, s86, s0
	s_cmp_gt_i32 s5, -1
	s_cbranch_scc0 .LBB0_742
	s_lshl_b32 s0, s5, 5
	s_mov_b64 s[2:3], 0

; #define PG8_STAGE(bufoff, gbase, voff) do { _Pragma("unroll") for (int _i = 0; _i < 2; ++_i) \
;         __builtin_amdgcn_global_load_lds((const unsigned*)((const char*)(gbase) + (voff)[_i]), (PG8_LAS unsigned*)(lds + (bufoff) + ldsw + _i * 8192), 16, 0, 0); } while (0)
; #define PG8_LDA(dst, b, h) do { _Pragma("unroll") for (int m = 0; m < 4; ++m) _Pragma("unroll") for (int k = 0; k < 2; ++k) dst[m][k] = *(const PG8_LAS bf16x8*)(lds + PG8_SA(b, h) + aoff + m * 2048 + k * 1024); } while (0)
; #define PG8_LDB(dst, b, h) do { _Pragma("unroll") for (int n = 0; n < 2; ++n) _Pragma("unroll") for (int k = 0; k < 2; ++k) dst[n][k] = *(const PG8_LAS bf16x8*)(lds + PG8_SB(b, h) + boff + n * 2048 + k * 1024); } while (0)
; #define PG8_MMA(ai, bj, At, Bt) do { __builtin_amdgcn_s_setprio(1); _Pragma("unroll") for (int m = 0; m < 4; ++m) _Pragma("unroll") for (int n = 0; n < 2; ++n) _Pragma("unroll") for (int k = 0; k < 2; ++k) \
;         acc[ai][bj][m][n] = __builtin_amdgcn_mfma_f32_16x16x32_bf16(Bt[n][k], At[m][k], acc[ai][bj][m][n], 0, 0, 0); __builtin_amdgcn_s_setprio(0); } while (0)
; #define PG8_WAIT_V(n) asm volatile("s_waitcnt vmcnt(" #n ")" ::: "memory")
; #define PG8_WAIT_L(n) asm volatile("s_waitcnt lgkmcnt(" #n ")" ::: "memory")
; #define PG8_BAR __builtin_amdgcn_s_barrier()
; #define PG8_SCHED __builtin_amdgcn_sched_barrier(0)
; template <class Epi, class Sched, bool ALIGN_EPI = false, bool SP2 = false>
; __device__ __forceinline__ void gemm_phase(PG8_LAS unsigned char* lds, const Gemm g, const Sched& S, const Epi& E, const int tid) {
;     ...
;             PG8_LDB(B0, 0, 0); PG8_LDB(B1, 0, 1); PG8_SCHED; PG8_LDA(At, 0, 0); PG8_STAGE(PG8_SA(1, 1), a1 + hstep, voffA);
;             PG8_WAIT_V(8); PG8_WAIT_L(0); PG8_BAR; PG8_MMA(0, 0, At, B0); PG8_MMA(0, 1, At, B1); PG8_BAR; PG8_SCHED;
;             PG8_LDA(At, 0, 1); PG8_STAGE(PG8_SB(0, 0), b2, voffB); PG8_STAGE(PG8_SB(0, 1), b2 + hstep, voffB); PG8_STAGE(PG8_SA(0, 0), a2, voffA);
;             PG8_WAIT_V(8); PG8_WAIT_L(0); PG8_BAR; PG8_MMA(1, 0, At, B0); PG8_MMA(1, 1, At, B1); PG8_BAR; PG8_SCHED;
.LBB0_760:
	s_add_u32 s14, s12, 0x100
	s_addc_u32 s15, s13, 0
	s_add_i32 s26, 0, 0x10000
	s_cmp_eq_u32 s33, 40
	s_cselect_b32 s39, s5, s15
	s_cselect_b32 s38, s4, s14
	v_add_u32_e32 v148, s26, v5
	s_cselect_b32 s37, s11, s19
	s_cselect_b32 s36, s10, s18
	s_add_i32 s27, 0, 0x14000
	ds_read_b128 v[144:147], v148
	ds_read_b128 v[152:155], v148 offset:1024
	ds_read_b128 v[164:167], v148 offset:2048
	ds_read_b128 v[168:171], v148 offset:3072
	v_add_u32_e32 v148, s27, v5
	ds_read_b128 v[172:175], v148
	ds_read_b128 v[176:179], v148 offset:1024
	ds_read_b128 v[180:183], v148 offset:2048
	ds_read_b128 v[184:187], v148 offset:3072
	v_lshl_add_u64 v[148:149], s[12:13], 0, v[140:141]
	s_add_i32 m0, s41, 0xc000
	ds_read_b128 v[188:191], v151
	ds_read_b128 v[192:195], v151 offset:1024
	ds_read_b128 v[196:199], v151 offset:2048
	ds_read_b128 v[200:203], v151 offset:3072
	ds_read_b128 v[204:207], v151 offset:4096
	ds_read_b128 v[208:211], v151 offset:5120
	ds_read_b128 v[218:221], v151 offset:6144
	ds_read_b128 v[222:225], v151 offset:7168
	global_load_lds_dwordx4 v[148:149], off
	v_lshl_add_u64 v[148:149], s[12:13], 0, v[142:143]
	s_add_i32 m0, s41, 0xe000
	s_nop 0
	global_load_lds_dwordx4 v[148:149], off
	s_waitcnt vmcnt(8)
	s_waitcnt lgkmcnt(0)
	s_barrier
	s_waitcnt lgkmcnt(0)
	v_mfma_f32_16x16x32_bf16 v[130:133], v[144:147], v[188:191], v[130:133]
	v_mfma_f32_16x16x32_bf16 v[126:129], v[164:167], v[188:191], v[126:129]
	v_mfma_f32_16x16x32_bf16 v[114:117], v[144:147], v[196:199], v[114:117]
	v_mfma_f32_16x16x32_bf16 v[110:113], v[164:167], v[196:199], v[110:113]
	v_mfma_f32_16x16x32_bf16 v[98:101], v[144:147], v[204:207], v[98:101]
	v_mfma_f32_16x16x32_bf16 v[94:97], v[164:167], v[204:207], v[94:97]
	v_mfma_f32_16x16x32_bf16 v[82:85], v[144:147], v[218:221], v[82:85]
	v_mfma_f32_16x16x32_bf16 v[78:81], v[164:167], v[218:221], v[78:81]
	v_mfma_f32_16x16x32_bf16 v[130:133], v[152:155], v[192:195], v[130:133]
	v_mfma_f32_16x16x32_bf16 v[126:129], v[168:171], v[192:195], v[126:129]
	v_mfma_f32_16x16x32_bf16 v[114:117], v[152:155], v[200:203], v[114:117]
	v_mfma_f32_16x16x32_bf16 v[110:113], v[168:171], v[200:203], v[110:113]
	v_mfma_f32_16x16x32_bf16 v[98:101], v[152:155], v[208:211], v[98:101]
	v_mfma_f32_16x16x32_bf16 v[94:97], v[168:171], v[208:211], v[94:97]
	v_mfma_f32_16x16x32_bf16 v[82:85], v[152:155], v[222:225], v[82:85]
	v_mfma_f32_16x16x32_bf16 v[78:81], v[168:171], v[222:225], v[78:81]
	v_mfma_f32_16x16x32_bf16 v[122:125], v[172:175], v[188:191], v[122:125]
	v_mfma_f32_16x16x32_bf16 v[118:121], v[180:183], v[188:191], v[118:121]
	v_mfma_f32_16x16x32_bf16 v[106:109], v[172:175], v[196:199], v[106:109]
	v_mfma_f32_16x16x32_bf16 v[102:105], v[180:183], v[196:199], v[102:105]
	v_mfma_f32_16x16x32_bf16 v[90:93], v[172:175], v[204:207], v[90:93]
	v_mfma_f32_16x16x32_bf16 v[86:89], v[180:183], v[204:207], v[86:89]
	v_mfma_f32_16x16x32_bf16 v[74:77], v[172:175], v[218:221], v[74:77]
	v_mfma_f32_16x16x32_bf16 v[70:73], v[180:183], v[218:221], v[70:73]
	v_mfma_f32_16x16x32_bf16 v[122:125], v[176:179], v[192:195], v[122:125]
	v_mfma_f32_16x16x32_bf16 v[118:121], v[184:187], v[192:195], v[118:121]
	v_mfma_f32_16x16x32_bf16 v[106:109], v[176:179], v[200:203], v[106:109]
	v_mfma_f32_16x16x32_bf16 v[102:105], v[184:187], v[200:203], v[102:105]
	v_mfma_f32_16x16x32_bf16 v[90:93], v[176:179], v[208:211], v[90:93]
	v_mfma_f32_16x16x32_bf16 v[86:89], v[184:187], v[208:211], v[86:89]
	v_mfma_f32_16x16x32_bf16 v[74:77], v[176:179], v[222:225], v[74:77]
	v_mfma_f32_16x16x32_bf16 v[70:73], v[184:187], v[222:225], v[70:73]
	s_barrier
	s_add_i32 s12, s26, s40
	v_lshl_add_u64 v[148:149], s[36:37], 0, v[134:135]
	s_mov_b32 m0, s12
	ds_read_b128 v[188:191], v151 offset:16384
	ds_read_b128 v[192:195], v151 offset:17408
	ds_read_b128 v[196:199], v151 offset:18432
	ds_read_b128 v[200:203], v151 offset:19456
	ds_read_b128 v[204:207], v151 offset:20480
	ds_read_b128 v[208:211], v151 offset:21504
	ds_read_b128 v[218:221], v151 offset:22528
	ds_read_b128 v[222:225], v151 offset:23552
	global_load_lds_dwordx4 v[148:149], off
	s_add_i32 m0, s12, 0x2000
	s_add_u32 s12, s36, 0xb0000
	v_lshl_add_u64 v[156:157], s[36:37], 0, v[138:139]
	s_addc_u32 s13, s37, 0
	s_add_i32 s26, s27, s40
	global_load_lds_dwordx4 v[156:157], off
	v_lshl_add_u64 v[160:161], s[12:13], 0, v[134:135]
	s_mov_b32 m0, s26
	v_lshl_add_u64 v[212:213], s[38:39], 0, v[136:137]
	global_load_lds_dwordx4 v[160:161], off
	v_lshl_add_u64 v[160:161], s[12:13], 0, v[138:139]
	s_add_i32 m0, s26, 0x2000
	s_nop 0
	global_load_lds_dwordx4 v[160:161], off
	v_lshl_add_u64 v[160:161], s[38:39], 0, v[2:3]
	s_mov_b32 m0, s41
	s_nop 0
	global_load_lds_dwordx4 v[160:161], off
	s_mov_b32 m0, s42
	s_nop 0
	global_load_lds_dwordx4 v[212:213], off
	s_waitcnt vmcnt(8)
	s_waitcnt lgkmcnt(0)
	s_barrier
; #define PG8_STAGE(bufoff, gbase, voff) do { _Pragma("unroll") for (int _i = 0; _i < 2; ++_i) \
;         __builtin_amdgcn_global_load_lds((const unsigned*)((const char*)(gbase) + (voff)[_i]), (PG8_LAS unsigned*)(lds + (bufoff) + ldsw + _i * 8192), 16, 0, 0); } while (0)
; #define PG8_LDA(dst, b, h) do { _Pragma("unroll") for (int m = 0; m < 4; ++m) _Pragma("unroll") for (int k = 0; k < 2; ++k) dst[m][k] = *(const PG8_LAS bf16x8*)(lds + PG8_SA(b, h) + aoff + m * 2048 + k * 1024); } while (0)
; #define PG8_LDB(dst, b, h) do { _Pragma("unroll") for (int n = 0; n < 2; ++n) _Pragma("unroll") for (int k = 0; k < 2; ++k) dst[n][k] = *(const PG8_LAS bf16x8*)(lds + PG8_SB(b, h) + boff + n * 2048 + k * 1024); } while (0)
; #define PG8_MMA(ai, bj, At, Bt) do { __builtin_amdgcn_s_setprio(1); _Pragma("unroll") for (int m = 0; m < 4; ++m) _Pragma("unroll") for (int n = 0; n < 2; ++n) _Pragma("unroll") for (int k = 0; k < 2; ++k) \
;         acc[ai][bj][m][n] = __builtin_amdgcn_mfma_f32_16x16x32_bf16(Bt[n][k], At[m][k], acc[ai][bj][m][n], 0, 0, 0); __builtin_amdgcn_s_setprio(0); } while (0)
; #define PG8_WAIT_V(n) asm volatile("s_waitcnt vmcnt(" #n ")" ::: "memory")
; #define PG8_WAIT_L(n) asm volatile("s_waitcnt lgkmcnt(" #n ")" ::: "memory")
; #define PG8_BAR __builtin_amdgcn_s_barrier()
; #define PG8_SCHED __builtin_amdgcn_sched_barrier(0)
; template <class Epi, class Sched, bool ALIGN_EPI = false, bool SP2 = false>
; __device__ __forceinline__ void gemm_phase(PG8_LAS unsigned char* lds, const Gemm g, const Sched& S, const Epi& E, const int tid) {
;     ...
;             PG8_WAIT_V(8); PG8_WAIT_L(0); PG8_BAR; PG8_MMA(1, 0, At, B0); PG8_MMA(1, 1, At, B1); PG8_BAR; PG8_SCHED;
;             PG8_LDB(B0, 1, 0); PG8_LDB(B1, 1, 1); PG8_SCHED; PG8_LDA(At, 1, 0); PG8_STAGE(PG8_SA(0, 1), a2 + hstep, voffA);
;             PG8_WAIT_V(8); PG8_WAIT_L(0); PG8_BAR; PG8_MMA(0, 0, At, B0); PG8_MMA(0, 1, At, B1); PG8_BAR; PG8_SCHED;
	s_waitcnt lgkmcnt(0)
	v_mfma_f32_16x16x32_bf16 v[66:69], v[144:147], v[188:191], v[66:69]
	v_mfma_f32_16x16x32_bf16 v[62:65], v[164:167], v[188:191], v[62:65]
	v_mfma_f32_16x16x32_bf16 v[50:53], v[144:147], v[196:199], v[50:53]
	v_mfma_f32_16x16x32_bf16 v[46:49], v[164:167], v[196:199], v[46:49]
	v_mfma_f32_16x16x32_bf16 v[34:37], v[144:147], v[204:207], v[34:37]
	v_mfma_f32_16x16x32_bf16 v[30:33], v[164:167], v[204:207], v[30:33]
	v_mfma_f32_16x16x32_bf16 v[18:21], v[144:147], v[218:221], v[18:21]
	v_mfma_f32_16x16x32_bf16 v[14:17], v[164:167], v[218:221], v[14:17]
	v_mfma_f32_16x16x32_bf16 v[66:69], v[152:155], v[192:195], v[66:69]
	v_mfma_f32_16x16x32_bf16 v[62:65], v[168:171], v[192:195], v[62:65]
	v_mfma_f32_16x16x32_bf16 v[50:53], v[152:155], v[200:203], v[50:53]
	v_mfma_f32_16x16x32_bf16 v[46:49], v[168:171], v[200:203], v[46:49]
	v_mfma_f32_16x16x32_bf16 v[34:37], v[152:155], v[208:211], v[34:37]
	v_mfma_f32_16x16x32_bf16 v[30:33], v[168:171], v[208:211], v[30:33]
	v_mfma_f32_16x16x32_bf16 v[18:21], v[152:155], v[222:225], v[18:21]
	v_mfma_f32_16x16x32_bf16 v[14:17], v[168:171], v[222:225], v[14:17]
	v_mfma_f32_16x16x32_bf16 v[58:61], v[172:175], v[188:191], v[58:61]
	v_mfma_f32_16x16x32_bf16 v[54:57], v[180:183], v[188:191], v[54:57]
	v_mfma_f32_16x16x32_bf16 v[42:45], v[172:175], v[196:199], v[42:45]
	v_mfma_f32_16x16x32_bf16 v[38:41], v[180:183], v[196:199], v[38:41]
	v_mfma_f32_16x16x32_bf16 v[26:29], v[172:175], v[204:207], v[26:29]
	v_mfma_f32_16x16x32_bf16 v[22:25], v[180:183], v[204:207], v[22:25]
	v_mfma_f32_16x16x32_bf16 v[10:13], v[172:175], v[218:221], v[10:13]
	v_mfma_f32_16x16x32_bf16 v[6:9], v[180:183], v[218:221], v[6:9]
	v_mfma_f32_16x16x32_bf16 v[58:61], v[176:179], v[192:195], v[58:61]
	v_mfma_f32_16x16x32_bf16 v[54:57], v[184:187], v[192:195], v[54:57]
	v_mfma_f32_16x16x32_bf16 v[42:45], v[176:179], v[200:203], v[42:45]
	v_mfma_f32_16x16x32_bf16 v[38:41], v[184:187], v[200:203], v[38:41]
	v_mfma_f32_16x16x32_bf16 v[26:29], v[176:179], v[208:211], v[26:29]
	v_mfma_f32_16x16x32_bf16 v[22:25], v[184:187], v[208:211], v[22:25]
	v_mfma_f32_16x16x32_bf16 v[10:13], v[176:179], v[222:225], v[10:13]
	v_mfma_f32_16x16x32_bf16 v[6:9], v[184:187], v[222:225], v[6:9]
	s_barrier
	s_add_i32 s26, 0, 0x18000
	v_add_u32_e32 v159, s26, v5
	s_add_i32 s27, 0, 0x1c000
	ds_read_b128 v[144:147], v159
	ds_read_b128 v[152:155], v159 offset:1024
	ds_read_b128 v[164:167], v159 offset:2048
	ds_read_b128 v[168:171], v159 offset:3072
	v_add_u32_e32 v159, s27, v5
	ds_read_b128 v[172:175], v159
	ds_read_b128 v[176:179], v159 offset:1024
	ds_read_b128 v[180:183], v159 offset:2048
	ds_read_b128 v[184:187], v159 offset:3072
	s_add_u32 s12, s38, 0xb0000
	s_addc_u32 s13, s39, 0
	s_mov_b32 m0, s43
	v_lshl_add_u64 v[214:215], s[12:13], 0, v[2:3]
	ds_read_b128 v[188:191], v151 offset:32768
	ds_read_b128 v[192:195], v151 offset:33792
	ds_read_b128 v[196:199], v151 offset:34816
	ds_read_b128 v[200:203], v151 offset:35840
	ds_read_b128 v[204:207], v151 offset:36864
	ds_read_b128 v[208:211], v151 offset:37888
	ds_read_b128 v[218:221], v151 offset:38912
	ds_read_b128 v[222:225], v151 offset:39936
	global_load_lds_dwordx4 v[214:215], off
	v_lshl_add_u64 v[214:215], s[12:13], 0, v[136:137]
	s_mov_b32 m0, s44
	s_nop 0
	global_load_lds_dwordx4 v[214:215], off
	s_waitcnt vmcnt(8)
	s_waitcnt lgkmcnt(0)
	s_barrier
	s_waitcnt lgkmcnt(0)
	v_mfma_f32_16x16x32_bf16 v[130:133], v[144:147], v[188:191], v[130:133]
	v_mfma_f32_16x16x32_bf16 v[126:129], v[164:167], v[188:191], v[126:129]
	v_mfma_f32_16x16x32_bf16 v[114:117], v[144:147], v[196:199], v[114:117]
	v_mfma_f32_16x16x32_bf16 v[110:113], v[164:167], v[196:199], v[110:113]
	v_mfma_f32_16x16x32_bf16 v[98:101], v[144:147], v[204:207], v[98:101]
	v_mfma_f32_16x16x32_bf16 v[94:97], v[164:167], v[204:207], v[94:97]
	v_mfma_f32_16x16x32_bf16 v[82:85], v[144:147], v[218:221], v[82:85]
	v_mfma_f32_16x16x32_bf16 v[78:81], v[164:167], v[218:221], v[78:81]
	v_mfma_f32_16x16x32_bf16 v[130:133], v[152:155], v[192:195], v[130:133]
	v_mfma_f32_16x16x32_bf16 v[126:129], v[168:171], v[192:195], v[126:129]
	v_mfma_f32_16x16x32_bf16 v[114:117], v[152:155], v[200:203], v[114:117]
	v_mfma_f32_16x16x32_bf16 v[110:113], v[168:171], v[200:203], v[110:113]
	v_mfma_f32_16x16x32_bf16 v[98:101], v[152:155], v[208:211], v[98:101]
	v_mfma_f32_16x16x32_bf16 v[94:97], v[168:171], v[208:211], v[94:97]
	v_mfma_f32_16x16x32_bf16 v[82:85], v[152:155], v[222:225], v[82:85]
	v_mfma_f32_16x16x32_bf16 v[78:81], v[168:171], v[222:225], v[78:81]
	v_mfma_f32_16x16x32_bf16 v[122:125], v[172:175], v[188:191], v[122:125]
	v_mfma_f32_16x16x32_bf16 v[118:121], v[180:183], v[188:191], v[118:121]
	v_mfma_f32_16x16x32_bf16 v[106:109], v[172:175], v[196:199], v[106:109]
	v_mfma_f32_16x16x32_bf16 v[102:105], v[180:183], v[196:199], v[102:105]
	v_mfma_f32_16x16x32_bf16 v[90:93], v[172:175], v[204:207], v[90:93]
	v_mfma_f32_16x16x32_bf16 v[86:89], v[180:183], v[204:207], v[86:89]
	v_mfma_f32_16x16x32_bf16 v[74:77], v[172:175], v[218:221], v[74:77]
	v_mfma_f32_16x16x32_bf16 v[70:73], v[180:183], v[218:221], v[70:73]
	v_mfma_f32_16x16x32_bf16 v[122:125], v[176:179], v[192:195], v[122:125]
	v_mfma_f32_16x16x32_bf16 v[118:121], v[184:187], v[192:195], v[118:121]
	v_mfma_f32_16x16x32_bf16 v[106:109], v[176:179], v[200:203], v[106:109]
	v_mfma_f32_16x16x32_bf16 v[102:105], v[184:187], v[200:203], v[102:105]
	v_mfma_f32_16x16x32_bf16 v[90:93], v[176:179], v[208:211], v[90:93]
	v_mfma_f32_16x16x32_bf16 v[86:89], v[184:187], v[208:211], v[86:89]
	v_mfma_f32_16x16x32_bf16 v[74:77], v[176:179], v[222:225], v[74:77]
	v_mfma_f32_16x16x32_bf16 v[70:73], v[184:187], v[222:225], v[70:73]
	s_barrier
; #define PG8_STAGE(bufoff, gbase, voff) do { _Pragma("unroll") for (int _i = 0; _i < 2; ++_i) \
;         __builtin_amdgcn_global_load_lds((const unsigned*)((const char*)(gbase) + (voff)[_i]), (PG8_LAS unsigned*)(lds + (bufoff) + ldsw + _i * 8192), 16, 0, 0); } while (0)
; #define PG8_LDA(dst, b, h) do { _Pragma("unroll") for (int m = 0; m < 4; ++m) _Pragma("unroll") for (int k = 0; k < 2; ++k) dst[m][k] = *(const PG8_LAS bf16x8*)(lds + PG8_SA(b, h) + aoff + m * 2048 + k * 1024); } while (0)
; #define PG8_MMA(ai, bj, At, Bt) do { __builtin_amdgcn_s_setprio(1); _Pragma("unroll") for (int m = 0; m < 4; ++m) _Pragma("unroll") for (int n = 0; n < 2; ++n) _Pragma("unroll") for (int k = 0; k < 2; ++k) \
;         acc[ai][bj][m][n] = __builtin_amdgcn_mfma_f32_16x16x32_bf16(Bt[n][k], At[m][k], acc[ai][bj][m][n], 0, 0, 0); __builtin_amdgcn_s_setprio(0); } while (0)
; #define PG8_WAIT_V(n) asm volatile("s_waitcnt vmcnt(" #n ")" ::: "memory")
; #define PG8_WAIT_L(n) asm volatile("s_waitcnt lgkmcnt(" #n ")" ::: "memory")
; #define PG8_BAR __builtin_amdgcn_s_barrier()
; #define PG8_SCHED __builtin_amdgcn_sched_barrier(0)
; template <class Epi, class Sched, bool ALIGN_EPI = false, bool SP2 = false>
; __device__ __forceinline__ void gemm_phase(PG8_LAS unsigned char* lds, const Gemm g, const Sched& S, const Epi& E, const int tid) {
;     ...
;             PG8_LDA(At, 1, 1); PG8_STAGE(PG8_SB(1, 0), b3, voffB); PG8_STAGE(PG8_SB(1, 1), b3 + hstep, voffB); PG8_STAGE(PG8_SA(1, 0), a3, voffA);
;             PG8_WAIT_V(8); PG8_WAIT_L(0); PG8_BAR; PG8_MMA(1, 0, At, B0); PG8_MMA(1, 1, At, B1); PG8_BAR; PG8_SCHED;
;     ...
;         if constexpr (ALIGN_EPI) { if (wr == 0) PG8_BAR; }
	s_add_i32 s12, s26, s40
	v_lshl_add_u64 v[148:149], v[148:149], 0, s[16:17]
	s_mov_b32 m0, s12
	ds_read_b128 v[188:191], v151 offset:49152
	ds_read_b128 v[192:195], v151 offset:50176
	ds_read_b128 v[196:199], v151 offset:51200
	ds_read_b128 v[200:203], v151 offset:52224
	ds_read_b128 v[204:207], v151 offset:53248
	ds_read_b128 v[208:211], v151 offset:54272
	ds_read_b128 v[218:221], v151 offset:55296
	ds_read_b128 v[222:225], v151 offset:56320
	global_load_lds_dwordx4 v[148:149], off
	s_add_i32 m0, s12, 0x2000
	s_add_u32 s12, s36, 0xb0080
	v_lshl_add_u64 v[148:149], v[156:157], 0, s[16:17]
	s_addc_u32 s13, s37, 0
	s_add_i32 s26, s27, s40
	global_load_lds_dwordx4 v[148:149], off
	v_lshl_add_u64 v[148:149], s[12:13], 0, v[134:135]
	s_mov_b32 m0, s26
	s_nop 0
	global_load_lds_dwordx4 v[148:149], off
	v_lshl_add_u64 v[148:149], s[12:13], 0, v[138:139]
	s_add_i32 m0, s26, 0x2000
	s_nop 0
	global_load_lds_dwordx4 v[148:149], off
	v_lshl_add_u64 v[148:149], v[160:161], 0, s[16:17]
	s_mov_b32 m0, s45
	s_nop 0
	global_load_lds_dwordx4 v[148:149], off
	v_lshl_add_u64 v[148:149], v[212:213], 0, s[16:17]
	s_mov_b32 m0, s46
	s_nop 0
	global_load_lds_dwordx4 v[148:149], off
	s_waitcnt vmcnt(8)
	s_waitcnt lgkmcnt(0)
	s_barrier
	s_waitcnt lgkmcnt(0)
	v_mfma_f32_16x16x32_bf16 v[66:69], v[144:147], v[188:191], v[66:69]
	v_mfma_f32_16x16x32_bf16 v[62:65], v[164:167], v[188:191], v[62:65]
	v_mfma_f32_16x16x32_bf16 v[50:53], v[144:147], v[196:199], v[50:53]
	v_mfma_f32_16x16x32_bf16 v[46:49], v[164:167], v[196:199], v[46:49]
	v_mfma_f32_16x16x32_bf16 v[34:37], v[144:147], v[204:207], v[34:37]
	v_mfma_f32_16x16x32_bf16 v[30:33], v[164:167], v[204:207], v[30:33]
	v_mfma_f32_16x16x32_bf16 v[18:21], v[144:147], v[218:221], v[18:21]
	v_mfma_f32_16x16x32_bf16 v[14:17], v[164:167], v[218:221], v[14:17]
	v_mfma_f32_16x16x32_bf16 v[66:69], v[152:155], v[192:195], v[66:69]
	v_mfma_f32_16x16x32_bf16 v[62:65], v[168:171], v[192:195], v[62:65]
	v_mfma_f32_16x16x32_bf16 v[50:53], v[152:155], v[200:203], v[50:53]
	v_mfma_f32_16x16x32_bf16 v[46:49], v[168:171], v[200:203], v[46:49]
	v_mfma_f32_16x16x32_bf16 v[34:37], v[152:155], v[208:211], v[34:37]
	v_mfma_f32_16x16x32_bf16 v[30:33], v[168:171], v[208:211], v[30:33]
	v_mfma_f32_16x16x32_bf16 v[18:21], v[152:155], v[222:225], v[18:21]
	v_mfma_f32_16x16x32_bf16 v[14:17], v[168:171], v[222:225], v[14:17]
	v_mfma_f32_16x16x32_bf16 v[58:61], v[172:175], v[188:191], v[58:61]
	v_mfma_f32_16x16x32_bf16 v[54:57], v[180:183], v[188:191], v[54:57]
	v_mfma_f32_16x16x32_bf16 v[42:45], v[172:175], v[196:199], v[42:45]
	v_mfma_f32_16x16x32_bf16 v[38:41], v[180:183], v[196:199], v[38:41]
	v_mfma_f32_16x16x32_bf16 v[26:29], v[172:175], v[204:207], v[26:29]
	v_mfma_f32_16x16x32_bf16 v[22:25], v[180:183], v[204:207], v[22:25]
	v_mfma_f32_16x16x32_bf16 v[10:13], v[172:175], v[218:221], v[10:13]
	v_mfma_f32_16x16x32_bf16 v[6:9], v[180:183], v[218:221], v[6:9]
	v_mfma_f32_16x16x32_bf16 v[58:61], v[176:179], v[192:195], v[58:61]
	v_mfma_f32_16x16x32_bf16 v[54:57], v[184:187], v[192:195], v[54:57]
	v_mfma_f32_16x16x32_bf16 v[42:45], v[176:179], v[200:203], v[42:45]
	v_mfma_f32_16x16x32_bf16 v[38:41], v[184:187], v[200:203], v[38:41]
	v_mfma_f32_16x16x32_bf16 v[26:29], v[176:179], v[208:211], v[26:29]
	v_mfma_f32_16x16x32_bf16 v[22:25], v[184:187], v[208:211], v[22:25]
	v_mfma_f32_16x16x32_bf16 v[10:13], v[176:179], v[222:225], v[10:13]
	v_mfma_f32_16x16x32_bf16 v[6:9], v[184:187], v[222:225], v[6:9]
	s_barrier
	s_add_i32 s33, s33, 2
	s_add_u32 s18, s18, 0x100
	s_addc_u32 s19, s19, 0
	s_cmp_gt_u32 s33, 41
	s_mov_b64 s[12:13], s[14:15]
	s_cbranch_scc0 .LBB0_760
	s_and_b64 vcc, exec, s[8:9]
	s_cbranch_vccz .LBB0_763
	s_barrier

; #define PG8_STAGE(bufoff, gbase, voff) do { _Pragma("unroll") for (int _i = 0; _i < 2; ++_i) \
;         __builtin_amdgcn_global_load_lds((const unsigned*)((const char*)(gbase) + (voff)[_i]), (PG8_LAS unsigned*)(lds + (bufoff) + ldsw + _i * 8192), 16, 0, 0); } while (0)
; #define PG8_LDA(dst, b, h) do { _Pragma("unroll") for (int m = 0; m < 4; ++m) _Pragma("unroll") for (int k = 0; k < 2; ++k) dst[m][k] = *(const PG8_LAS bf16x8*)(lds + PG8_SA(b, h) + aoff + m * 2048 + k * 1024); } while (0)
; #define PG8_LDB(dst, b, h) do { _Pragma("unroll") for (int n = 0; n < 2; ++n) _Pragma("unroll") for (int k = 0; k < 2; ++k) dst[n][k] = *(const PG8_LAS bf16x8*)(lds + PG8_SB(b, h) + boff + n * 2048 + k * 1024); } while (0)
; #define PG8_MMA(ai, bj, At, Bt) do { __builtin_amdgcn_s_setprio(1); _Pragma("unroll") for (int m = 0; m < 4; ++m) _Pragma("unroll") for (int n = 0; n < 2; ++n) _Pragma("unroll") for (int k = 0; k < 2; ++k) \
;         acc[ai][bj][m][n] = __builtin_amdgcn_mfma_f32_16x16x32_bf16(Bt[n][k], At[m][k], acc[ai][bj][m][n], 0, 0, 0); __builtin_amdgcn_s_setprio(0); } while (0)
; #define PG8_WAIT_V(n) asm volatile("s_waitcnt vmcnt(" #n ")" ::: "memory")
; #define PG8_WAIT_L(n) asm volatile("s_waitcnt lgkmcnt(" #n ")" ::: "memory")
; #define PG8_BAR __builtin_amdgcn_s_barrier()
; #define PG8_SCHED __builtin_amdgcn_sched_barrier(0)
; template <class Epi, class Sched, bool ALIGN_EPI = false, bool SP2 = false>
; __device__ __forceinline__ void gemm_phase(PG8_LAS unsigned char* lds, const Gemm g, const Sched& S, const Epi& E, const int tid) {
;     ...
;             const bool last = (t == nt - 2);
;             const char* a1 = cA + (size_t)(t + 1) * kstep;
;             const char* a2 = last ? nA : cA + (size_t)(t + 2) * kstep; const char* b2 = last ? nB : cB + (size_t)(t + 2) * kstep;
;             const char* a3 = a2 + kstep; const char* b3 = b2 + kstep;
;             if (last && has_next) S.a_ready(nxt);
;             if constexpr (SP2) {
;             PG8_LDB(B0, 0, 0); PG8_LDB(B1, 0, 1); PG8_SCHED; PG8_LDA(At, 0, 0); PG8_STAGE(PG8_SA(1, 1), a1 + hstep, voffA);
;             PG8_WAIT_V(8); PG8_WAIT_L(0); PG8_BAR; PG8_MMA(0, 0, At, B0); PG8_MMA(0, 1, At, B1); PG8_BAR; PG8_SCHED;
;             PG8_LDA(At, 0, 1); PG8_STAGE(PG8_SB(0, 0), b2, voffB); PG8_STAGE(PG8_SB(0, 1), b2 + hstep, voffB); PG8_STAGE(PG8_SA(0, 0), a2, voffA);
.LBB0_792:
	s_add_u32 s40, s38, 0x100
	s_addc_u32 s41, s39, 0
	s_add_i32 s26, 0, 0x10000
	s_cmp_eq_u32 s19, 40
	s_cselect_b32 s45, s9, s41
	s_cselect_b32 s44, s8, s40
	v_add_u32_e32 v148, s26, v5
	s_cselect_b32 s43, s15, s18
	s_cselect_b32 s42, s14, s1
	s_add_i32 s27, 0, 0x14000
	ds_read_b128 v[144:147], v148
	ds_read_b128 v[174:177], v148 offset:1024
	ds_read_b128 v[178:181], v148 offset:2048
	ds_read_b128 v[182:185], v148 offset:3072
	v_add_u32_e32 v148, s27, v5
	ds_read_b128 v[186:189], v148
	ds_read_b128 v[190:193], v148 offset:1024
	ds_read_b128 v[194:197], v148 offset:2048
	ds_read_b128 v[198:201], v148 offset:3072
	v_lshl_add_u64 v[148:149], s[38:39], 0, v[140:141]
	s_add_i32 m0, s46, 0xc000
	ds_read_b128 v[202:205], v167
	ds_read_b128 v[206:209], v167 offset:1024
	ds_read_b128 v[210:213], v167 offset:2048
	ds_read_b128 v[218:221], v167 offset:3072
	ds_read_b128 v[222:225], v167 offset:4096
	ds_read_b128 v[226:229], v167 offset:5120
	ds_read_b128 v[230:233], v167 offset:6144
	ds_read_b128 v[234:237], v167 offset:7168
	global_load_lds_dwordx4 v[148:149], off
	v_lshl_add_u64 v[148:149], s[38:39], 0, v[142:143]
	s_add_i32 m0, s46, 0xe000
	s_nop 0
	global_load_lds_dwordx4 v[148:149], off
	s_waitcnt vmcnt(8)
	s_waitcnt lgkmcnt(0)
	s_barrier
	s_waitcnt lgkmcnt(0)
	v_mfma_f32_16x16x32_bf16 v[130:133], v[144:147], v[202:205], v[130:133]
	v_mfma_f32_16x16x32_bf16 v[126:129], v[178:181], v[202:205], v[126:129]
	v_mfma_f32_16x16x32_bf16 v[114:117], v[144:147], v[210:213], v[114:117]
	v_mfma_f32_16x16x32_bf16 v[110:113], v[178:181], v[210:213], v[110:113]
	v_mfma_f32_16x16x32_bf16 v[98:101], v[144:147], v[222:225], v[98:101]
	v_mfma_f32_16x16x32_bf16 v[94:97], v[178:181], v[222:225], v[94:97]
	v_mfma_f32_16x16x32_bf16 v[82:85], v[144:147], v[230:233], v[82:85]
	v_mfma_f32_16x16x32_bf16 v[78:81], v[178:181], v[230:233], v[78:81]
	v_mfma_f32_16x16x32_bf16 v[130:133], v[174:177], v[206:209], v[130:133]
	v_mfma_f32_16x16x32_bf16 v[126:129], v[182:185], v[206:209], v[126:129]
	v_mfma_f32_16x16x32_bf16 v[114:117], v[174:177], v[218:221], v[114:117]
	v_mfma_f32_16x16x32_bf16 v[110:113], v[182:185], v[218:221], v[110:113]
	v_mfma_f32_16x16x32_bf16 v[98:101], v[174:177], v[226:229], v[98:101]
	v_mfma_f32_16x16x32_bf16 v[94:97], v[182:185], v[226:229], v[94:97]
	v_mfma_f32_16x16x32_bf16 v[82:85], v[174:177], v[234:237], v[82:85]
	v_mfma_f32_16x16x32_bf16 v[78:81], v[182:185], v[234:237], v[78:81]
	v_mfma_f32_16x16x32_bf16 v[122:125], v[186:189], v[202:205], v[122:125]
	v_mfma_f32_16x16x32_bf16 v[118:121], v[194:197], v[202:205], v[118:121]
	v_mfma_f32_16x16x32_bf16 v[106:109], v[186:189], v[210:213], v[106:109]
	v_mfma_f32_16x16x32_bf16 v[102:105], v[194:197], v[210:213], v[102:105]
	v_mfma_f32_16x16x32_bf16 v[90:93], v[186:189], v[222:225], v[90:93]
	v_mfma_f32_16x16x32_bf16 v[86:89], v[194:197], v[222:225], v[86:89]
	v_mfma_f32_16x16x32_bf16 v[74:77], v[186:189], v[230:233], v[74:77]
	v_mfma_f32_16x16x32_bf16 v[70:73], v[194:197], v[230:233], v[70:73]
	v_mfma_f32_16x16x32_bf16 v[122:125], v[190:193], v[206:209], v[122:125]
	v_mfma_f32_16x16x32_bf16 v[118:121], v[198:201], v[206:209], v[118:121]
	v_mfma_f32_16x16x32_bf16 v[106:109], v[190:193], v[218:221], v[106:109]
	v_mfma_f32_16x16x32_bf16 v[102:105], v[198:201], v[218:221], v[102:105]
	v_mfma_f32_16x16x32_bf16 v[90:93], v[190:193], v[226:229], v[90:93]
	v_mfma_f32_16x16x32_bf16 v[86:89], v[198:201], v[226:229], v[86:89]
	v_mfma_f32_16x16x32_bf16 v[74:77], v[190:193], v[234:237], v[74:77]
	v_mfma_f32_16x16x32_bf16 v[70:73], v[198:201], v[234:237], v[70:73]
	s_barrier
	s_add_i32 s26, s26, s20
	v_lshl_add_u64 v[148:149], s[42:43], 0, v[134:135]
	s_mov_b32 m0, s26
	ds_read_b128 v[202:205], v167 offset:16384
	ds_read_b128 v[206:209], v167 offset:17408
	ds_read_b128 v[210:213], v167 offset:18432
	ds_read_b128 v[218:221], v167 offset:19456
	ds_read_b128 v[222:225], v167 offset:20480
	ds_read_b128 v[226:229], v167 offset:21504
	ds_read_b128 v[230:233], v167 offset:22528
	ds_read_b128 v[234:237], v167 offset:23552
	global_load_lds_dwordx4 v[148:149], off
	s_add_i32 m0, s26, 0x2000
	s_add_u32 s34, s42, 0xb0000
	v_lshl_add_u64 v[160:161], s[42:43], 0, v[138:139]
	s_addc_u32 s35, s43, 0
	s_add_i32 s26, s27, s20
	global_load_lds_dwordx4 v[160:161], off
	v_lshl_add_u64 v[214:215], s[34:35], 0, v[134:135]
	s_mov_b32 m0, s26
	v_lshl_add_u64 v[238:239], s[44:45], 0, v[136:137]
	global_load_lds_dwordx4 v[214:215], off
	v_lshl_add_u64 v[214:215], s[34:35], 0, v[138:139]
	s_add_i32 m0, s26, 0x2000
	s_nop 0
	global_load_lds_dwordx4 v[214:215], off
	v_lshl_add_u64 v[214:215], s[44:45], 0, v[2:3]
	s_mov_b32 m0, s46
	s_nop 0
	global_load_lds_dwordx4 v[214:215], off
	s_mov_b32 m0, s47
	s_nop 0
	global_load_lds_dwordx4 v[238:239], off
	s_waitcnt vmcnt(8)
	s_waitcnt lgkmcnt(0)
	s_barrier
; #define PG8_STAGE(bufoff, gbase, voff) do { _Pragma("unroll") for (int _i = 0; _i < 2; ++_i) \
;         __builtin_amdgcn_global_load_lds((const unsigned*)((const char*)(gbase) + (voff)[_i]), (PG8_LAS unsigned*)(lds + (bufoff) + ldsw + _i * 8192), 16, 0, 0); } while (0)
; #define PG8_LDA(dst, b, h) do { _Pragma("unroll") for (int m = 0; m < 4; ++m) _Pragma("unroll") for (int k = 0; k < 2; ++k) dst[m][k] = *(const PG8_LAS bf16x8*)(lds + PG8_SA(b, h) + aoff + m * 2048 + k * 1024); } while (0)
; #define PG8_LDB(dst, b, h) do { _Pragma("unroll") for (int n = 0; n < 2; ++n) _Pragma("unroll") for (int k = 0; k < 2; ++k) dst[n][k] = *(const PG8_LAS bf16x8*)(lds + PG8_SB(b, h) + boff + n * 2048 + k * 1024); } while (0)
; #define PG8_MMA(ai, bj, At, Bt) do { __builtin_amdgcn_s_setprio(1); _Pragma("unroll") for (int m = 0; m < 4; ++m) _Pragma("unroll") for (int n = 0; n < 2; ++n) _Pragma("unroll") for (int k = 0; k < 2; ++k) \
;         acc[ai][bj][m][n] = __builtin_amdgcn_mfma_f32_16x16x32_bf16(Bt[n][k], At[m][k], acc[ai][bj][m][n], 0, 0, 0); __builtin_amdgcn_s_setprio(0); } while (0)
; #define PG8_WAIT_V(n) asm volatile("s_waitcnt vmcnt(" #n ")" ::: "memory")
; #define PG8_WAIT_L(n) asm volatile("s_waitcnt lgkmcnt(" #n ")" ::: "memory")
; #define PG8_BAR __builtin_amdgcn_s_barrier()
; #define PG8_SCHED __builtin_amdgcn_sched_barrier(0)
; template <class Epi, class Sched, bool ALIGN_EPI = false, bool SP2 = false>
; __device__ __forceinline__ void gemm_phase(PG8_LAS unsigned char* lds, const Gemm g, const Sched& S, const Epi& E, const int tid) {
;     ...
;             PG8_WAIT_V(8); PG8_WAIT_L(0); PG8_BAR; PG8_MMA(1, 0, At, B0); PG8_MMA(1, 1, At, B1); PG8_BAR; PG8_SCHED;
;             PG8_LDB(B0, 1, 0); PG8_LDB(B1, 1, 1); PG8_SCHED; PG8_LDA(At, 1, 0); PG8_STAGE(PG8_SA(0, 1), a2 + hstep, voffA);
;             PG8_WAIT_V(8); PG8_WAIT_L(0); PG8_BAR; PG8_MMA(0, 0, At, B0); PG8_MMA(0, 1, At, B1); PG8_BAR; PG8_SCHED;
	s_waitcnt lgkmcnt(0)
	v_mfma_f32_16x16x32_bf16 v[66:69], v[144:147], v[202:205], v[66:69]
	v_mfma_f32_16x16x32_bf16 v[62:65], v[178:181], v[202:205], v[62:65]
	v_mfma_f32_16x16x32_bf16 v[50:53], v[144:147], v[210:213], v[50:53]
	v_mfma_f32_16x16x32_bf16 v[46:49], v[178:181], v[210:213], v[46:49]
	v_mfma_f32_16x16x32_bf16 v[34:37], v[144:147], v[222:225], v[34:37]
	v_mfma_f32_16x16x32_bf16 v[30:33], v[178:181], v[222:225], v[30:33]
	v_mfma_f32_16x16x32_bf16 v[18:21], v[144:147], v[230:233], v[18:21]
	v_mfma_f32_16x16x32_bf16 v[14:17], v[178:181], v[230:233], v[14:17]
	v_mfma_f32_16x16x32_bf16 v[66:69], v[174:177], v[206:209], v[66:69]
	v_mfma_f32_16x16x32_bf16 v[62:65], v[182:185], v[206:209], v[62:65]
	v_mfma_f32_16x16x32_bf16 v[50:53], v[174:177], v[218:221], v[50:53]
	v_mfma_f32_16x16x32_bf16 v[46:49], v[182:185], v[218:221], v[46:49]
	v_mfma_f32_16x16x32_bf16 v[34:37], v[174:177], v[226:229], v[34:37]
	v_mfma_f32_16x16x32_bf16 v[30:33], v[182:185], v[226:229], v[30:33]
	v_mfma_f32_16x16x32_bf16 v[18:21], v[174:177], v[234:237], v[18:21]
	v_mfma_f32_16x16x32_bf16 v[14:17], v[182:185], v[234:237], v[14:17]
	v_mfma_f32_16x16x32_bf16 v[58:61], v[186:189], v[202:205], v[58:61]
	v_mfma_f32_16x16x32_bf16 v[54:57], v[194:197], v[202:205], v[54:57]
	v_mfma_f32_16x16x32_bf16 v[42:45], v[186:189], v[210:213], v[42:45]
	v_mfma_f32_16x16x32_bf16 v[38:41], v[194:197], v[210:213], v[38:41]
	v_mfma_f32_16x16x32_bf16 v[26:29], v[186:189], v[222:225], v[26:29]
	v_mfma_f32_16x16x32_bf16 v[22:25], v[194:197], v[222:225], v[22:25]
	v_mfma_f32_16x16x32_bf16 v[10:13], v[186:189], v[230:233], v[10:13]
	v_mfma_f32_16x16x32_bf16 v[6:9], v[194:197], v[230:233], v[6:9]
	v_mfma_f32_16x16x32_bf16 v[58:61], v[190:193], v[206:209], v[58:61]
	v_mfma_f32_16x16x32_bf16 v[54:57], v[198:201], v[206:209], v[54:57]
	v_mfma_f32_16x16x32_bf16 v[42:45], v[190:193], v[218:221], v[42:45]
	v_mfma_f32_16x16x32_bf16 v[38:41], v[198:201], v[218:221], v[38:41]
	v_mfma_f32_16x16x32_bf16 v[26:29], v[190:193], v[226:229], v[26:29]
	v_mfma_f32_16x16x32_bf16 v[22:25], v[198:201], v[226:229], v[22:25]
	v_mfma_f32_16x16x32_bf16 v[10:13], v[190:193], v[234:237], v[10:13]
	v_mfma_f32_16x16x32_bf16 v[6:9], v[198:201], v[234:237], v[6:9]
	s_barrier
	s_add_i32 s26, 0, 0x18000
	s_add_i32 s27, 0, 0x1c000
	v_add_u32_e32 v182, s26, v5
	v_add_u32_e32 v198, s27, v5
	ds_read_b128 v[144:147], v182
	ds_read_b128 v[174:177], v182 offset:1024
	ds_read_b128 v[178:181], v182 offset:2048
	ds_read_b128 v[182:185], v182 offset:3072
	ds_read_b128 v[186:189], v198
	ds_read_b128 v[190:193], v198 offset:1024
	ds_read_b128 v[194:197], v198 offset:2048
	ds_read_b128 v[198:201], v198 offset:3072
	s_add_u32 s34, s44, 0xb0000
	s_addc_u32 s35, s45, 0
	s_mov_b32 m0, s48
	v_lshl_add_u64 v[240:241], s[34:35], 0, v[2:3]
	ds_read_b128 v[202:205], v167 offset:32768
	ds_read_b128 v[206:209], v167 offset:33792
	ds_read_b128 v[210:213], v167 offset:34816
	ds_read_b128 v[218:221], v167 offset:35840
	ds_read_b128 v[222:225], v167 offset:36864
	ds_read_b128 v[226:229], v167 offset:37888
	ds_read_b128 v[230:233], v167 offset:38912
	ds_read_b128 v[234:237], v167 offset:39936
	global_load_lds_dwordx4 v[240:241], off
	v_lshl_add_u64 v[240:241], s[34:35], 0, v[136:137]
	s_mov_b32 m0, s49
	s_nop 0
	global_load_lds_dwordx4 v[240:241], off
	s_waitcnt vmcnt(8)
	s_waitcnt lgkmcnt(0)
	s_barrier
	s_waitcnt lgkmcnt(0)
	v_mfma_f32_16x16x32_bf16 v[130:133], v[144:147], v[202:205], v[130:133]
	v_mfma_f32_16x16x32_bf16 v[126:129], v[178:181], v[202:205], v[126:129]
	v_mfma_f32_16x16x32_bf16 v[114:117], v[144:147], v[210:213], v[114:117]
	v_mfma_f32_16x16x32_bf16 v[110:113], v[178:181], v[210:213], v[110:113]
	v_mfma_f32_16x16x32_bf16 v[98:101], v[144:147], v[222:225], v[98:101]
	v_mfma_f32_16x16x32_bf16 v[94:97], v[178:181], v[222:225], v[94:97]
	v_mfma_f32_16x16x32_bf16 v[82:85], v[144:147], v[230:233], v[82:85]
	v_mfma_f32_16x16x32_bf16 v[78:81], v[178:181], v[230:233], v[78:81]
	v_mfma_f32_16x16x32_bf16 v[130:133], v[174:177], v[206:209], v[130:133]
	v_mfma_f32_16x16x32_bf16 v[126:129], v[182:185], v[206:209], v[126:129]
	v_mfma_f32_16x16x32_bf16 v[114:117], v[174:177], v[218:221], v[114:117]
	v_mfma_f32_16x16x32_bf16 v[110:113], v[182:185], v[218:221], v[110:113]
	v_mfma_f32_16x16x32_bf16 v[98:101], v[174:177], v[226:229], v[98:101]
	v_mfma_f32_16x16x32_bf16 v[94:97], v[182:185], v[226:229], v[94:97]
	v_mfma_f32_16x16x32_bf16 v[82:85], v[174:177], v[234:237], v[82:85]
	v_mfma_f32_16x16x32_bf16 v[78:81], v[182:185], v[234:237], v[78:81]
	v_mfma_f32_16x16x32_bf16 v[122:125], v[186:189], v[202:205], v[122:125]
	v_mfma_f32_16x16x32_bf16 v[118:121], v[194:197], v[202:205], v[118:121]
	v_mfma_f32_16x16x32_bf16 v[106:109], v[186:189], v[210:213], v[106:109]
	v_mfma_f32_16x16x32_bf16 v[102:105], v[194:197], v[210:213], v[102:105]
	v_mfma_f32_16x16x32_bf16 v[90:93], v[186:189], v[222:225], v[90:93]
	v_mfma_f32_16x16x32_bf16 v[86:89], v[194:197], v[222:225], v[86:89]
	v_mfma_f32_16x16x32_bf16 v[74:77], v[186:189], v[230:233], v[74:77]
	v_mfma_f32_16x16x32_bf16 v[70:73], v[194:197], v[230:233], v[70:73]
	v_mfma_f32_16x16x32_bf16 v[122:125], v[190:193], v[206:209], v[122:125]
	v_mfma_f32_16x16x32_bf16 v[118:121], v[198:201], v[206:209], v[118:121]
	v_mfma_f32_16x16x32_bf16 v[106:109], v[190:193], v[218:221], v[106:109]
	v_mfma_f32_16x16x32_bf16 v[102:105], v[198:201], v[218:221], v[102:105]
	v_mfma_f32_16x16x32_bf16 v[90:93], v[190:193], v[226:229], v[90:93]
	v_mfma_f32_16x16x32_bf16 v[86:89], v[198:201], v[226:229], v[86:89]
	v_mfma_f32_16x16x32_bf16 v[74:77], v[190:193], v[234:237], v[74:77]
	v_mfma_f32_16x16x32_bf16 v[70:73], v[198:201], v[234:237], v[70:73]
	s_barrier
; #define PG8_STAGE(bufoff, gbase, voff) do { _Pragma("unroll") for (int _i = 0; _i < 2; ++_i) \
;         __builtin_amdgcn_global_load_lds((const unsigned*)((const char*)(gbase) + (voff)[_i]), (PG8_LAS unsigned*)(lds + (bufoff) + ldsw + _i * 8192), 16, 0, 0); } while (0)
; #define PG8_LDA(dst, b, h) do { _Pragma("unroll") for (int m = 0; m < 4; ++m) _Pragma("unroll") for (int k = 0; k < 2; ++k) dst[m][k] = *(const PG8_LAS bf16x8*)(lds + PG8_SA(b, h) + aoff + m * 2048 + k * 1024); } while (0)
; #define PG8_MMA(ai, bj, At, Bt) do { __builtin_amdgcn_s_setprio(1); _Pragma("unroll") for (int m = 0; m < 4; ++m) _Pragma("unroll") for (int n = 0; n < 2; ++n) _Pragma("unroll") for (int k = 0; k < 2; ++k) \
;         acc[ai][bj][m][n] = __builtin_amdgcn_mfma_f32_16x16x32_bf16(Bt[n][k], At[m][k], acc[ai][bj][m][n], 0, 0, 0); __builtin_amdgcn_s_setprio(0); } while (0)
; #define PG8_WAIT_V(n) asm volatile("s_waitcnt vmcnt(" #n ")" ::: "memory")
; #define PG8_WAIT_L(n) asm volatile("s_waitcnt lgkmcnt(" #n ")" ::: "memory")
; #define PG8_BAR __builtin_amdgcn_s_barrier()
; #define PG8_SCHED __builtin_amdgcn_sched_barrier(0)
; template <class Epi, class Sched, bool ALIGN_EPI = false, bool SP2 = false>
; __device__ __forceinline__ void gemm_phase(PG8_LAS unsigned char* lds, const Gemm g, const Sched& S, const Epi& E, const int tid) {
;     ...
;             PG8_LDA(At, 1, 1); PG8_STAGE(PG8_SB(1, 0), b3, voffB); PG8_STAGE(PG8_SB(1, 1), b3 + hstep, voffB); PG8_STAGE(PG8_SA(1, 0), a3, voffA);
;             PG8_WAIT_V(8); PG8_WAIT_L(0); PG8_BAR; PG8_MMA(1, 0, At, B0); PG8_MMA(1, 1, At, B1); PG8_BAR; PG8_SCHED;
;     ...
;         if constexpr (ALIGN_EPI) { if (wr == 0) PG8_BAR; }
	s_add_i32 s26, s26, s20
	v_lshl_add_u64 v[148:149], v[148:149], 0, s[16:17]
	s_mov_b32 m0, s26
	ds_read_b128 v[202:205], v167 offset:49152
	ds_read_b128 v[206:209], v167 offset:50176
	ds_read_b128 v[210:213], v167 offset:51200
	ds_read_b128 v[218:221], v167 offset:52224
	ds_read_b128 v[222:225], v167 offset:53248
	ds_read_b128 v[226:229], v167 offset:54272
	ds_read_b128 v[230:233], v167 offset:55296
	ds_read_b128 v[234:237], v167 offset:56320
	global_load_lds_dwordx4 v[148:149], off
	s_add_i32 m0, s26, 0x2000
	s_add_u32 s34, s42, 0xb0080
	v_lshl_add_u64 v[148:149], v[160:161], 0, s[16:17]
	s_addc_u32 s35, s43, 0
	s_add_i32 s26, s27, s20
	global_load_lds_dwordx4 v[148:149], off
	v_lshl_add_u64 v[148:149], s[34:35], 0, v[134:135]
	s_mov_b32 m0, s26
	s_nop 0
	global_load_lds_dwordx4 v[148:149], off
	v_lshl_add_u64 v[148:149], s[34:35], 0, v[138:139]
	s_add_i32 m0, s26, 0x2000
	s_nop 0
	global_load_lds_dwordx4 v[148:149], off
	v_lshl_add_u64 v[148:149], v[214:215], 0, s[16:17]
	s_mov_b32 m0, s50
	s_nop 0
	global_load_lds_dwordx4 v[148:149], off
	v_lshl_add_u64 v[148:149], v[238:239], 0, s[16:17]
	s_mov_b32 m0, s51
	s_nop 0
	global_load_lds_dwordx4 v[148:149], off
	s_waitcnt vmcnt(8)
	s_waitcnt lgkmcnt(0)
	s_barrier
	s_waitcnt lgkmcnt(0)
	v_mfma_f32_16x16x32_bf16 v[66:69], v[144:147], v[202:205], v[66:69]
	v_mfma_f32_16x16x32_bf16 v[62:65], v[178:181], v[202:205], v[62:65]
	v_mfma_f32_16x16x32_bf16 v[50:53], v[144:147], v[210:213], v[50:53]
	v_mfma_f32_16x16x32_bf16 v[46:49], v[178:181], v[210:213], v[46:49]
	v_mfma_f32_16x16x32_bf16 v[34:37], v[144:147], v[222:225], v[34:37]
	v_mfma_f32_16x16x32_bf16 v[30:33], v[178:181], v[222:225], v[30:33]
	v_mfma_f32_16x16x32_bf16 v[18:21], v[144:147], v[230:233], v[18:21]
	v_mfma_f32_16x16x32_bf16 v[14:17], v[178:181], v[230:233], v[14:17]
	v_mfma_f32_16x16x32_bf16 v[66:69], v[174:177], v[206:209], v[66:69]
	v_mfma_f32_16x16x32_bf16 v[62:65], v[182:185], v[206:209], v[62:65]
	v_mfma_f32_16x16x32_bf16 v[50:53], v[174:177], v[218:221], v[50:53]
	v_mfma_f32_16x16x32_bf16 v[46:49], v[182:185], v[218:221], v[46:49]
	v_mfma_f32_16x16x32_bf16 v[34:37], v[174:177], v[226:229], v[34:37]
	v_mfma_f32_16x16x32_bf16 v[30:33], v[182:185], v[226:229], v[30:33]
	v_mfma_f32_16x16x32_bf16 v[18:21], v[174:177], v[234:237], v[18:21]
	v_mfma_f32_16x16x32_bf16 v[14:17], v[182:185], v[234:237], v[14:17]
	v_mfma_f32_16x16x32_bf16 v[58:61], v[186:189], v[202:205], v[58:61]
	v_mfma_f32_16x16x32_bf16 v[54:57], v[194:197], v[202:205], v[54:57]
	v_mfma_f32_16x16x32_bf16 v[42:45], v[186:189], v[210:213], v[42:45]
	v_mfma_f32_16x16x32_bf16 v[38:41], v[194:197], v[210:213], v[38:41]
	v_mfma_f32_16x16x32_bf16 v[26:29], v[186:189], v[222:225], v[26:29]
	v_mfma_f32_16x16x32_bf16 v[22:25], v[194:197], v[222:225], v[22:25]
	v_mfma_f32_16x16x32_bf16 v[10:13], v[186:189], v[230:233], v[10:13]
	v_mfma_f32_16x16x32_bf16 v[6:9], v[194:197], v[230:233], v[6:9]
	v_mfma_f32_16x16x32_bf16 v[58:61], v[190:193], v[206:209], v[58:61]
	v_mfma_f32_16x16x32_bf16 v[54:57], v[198:201], v[206:209], v[54:57]
	v_mfma_f32_16x16x32_bf16 v[42:45], v[190:193], v[218:221], v[42:45]
	v_mfma_f32_16x16x32_bf16 v[38:41], v[198:201], v[218:221], v[38:41]
	v_mfma_f32_16x16x32_bf16 v[26:29], v[190:193], v[226:229], v[26:29]
	v_mfma_f32_16x16x32_bf16 v[22:25], v[198:201], v[226:229], v[22:25]
	v_mfma_f32_16x16x32_bf16 v[10:13], v[190:193], v[234:237], v[10:13]
	v_mfma_f32_16x16x32_bf16 v[6:9], v[198:201], v[234:237], v[6:9]
	s_barrier
	s_add_i32 s19, s19, 2
	s_add_u32 s1, s1, 0x100
	s_addc_u32 s18, s18, 0
	s_cmp_gt_u32 s19, 41
	s_mov_b64 s[38:39], s[40:41]
	s_cbranch_scc0 .LBB0_792
	s_and_b64 vcc, exec, s[12:13]
	s_cbranch_vccz .LBB0_795
	s_barrier

; DI unsigned pk(float lo, float hi) { return pg8::cvt_pk_bf16(lo, hi); }
; DI void phase_xcast(const float* x, bf16* H, float* slots, int bid, int nb, int tid) {
;     const int wave = tid >> 6, lane = tid & 63;
;     for (int row = bid * 8 + wave; row < MG; row += nb * 8) {
;         const float4* xr = (const float4*)(x + (size_t)row * DM); float4 v[4]; float ss = 0.f;
; #pragma unroll
;         for (int q = 0; q < 4; ++q) { v[q] = xr[lane + 64 * q]; ss += v[q].x * v[q].x + v[q].y * v[q].y + v[q].z * v[q].z + v[q].w * v[q].w; }
; #pragma unroll
;         for (int o = 32; o >= 1; o >>= 1) ss += __shfl_xor(ss, o);
; #pragma unroll
;         for (int q = 0; q < 4; ++q) { uint2 w; w.x = pk(v[q].x, v[q].y); w.y = pk(v[q].z, v[q].w); *(uint2*)(H + (size_t)row * DM + (lane + 64 * q) * 4) = w; }
;         if (lane == 0) *(float4*)(slots + (size_t)row * 4) = make_float4(ss, 0.f, 0.f, 0.f);
.LBB0_817:
	s_setprio 0
	v_readlane_b32 s26, v255, 1
	v_readlane_b32 s27, v255, 2
	s_and_b64 s[0:1], s[88:89], s[26:27]
	s_andn2_b64 vcc, exec, s[0:1]
	s_movk_i32 s18, 0x3fff
	s_cbranch_vccnz .LBB0_824
	s_lshl_b32 s8, s86, 3
	v_ashrrev_i32_e32 v2, 6, v158
	v_add_u32_e32 v1, s8, v2
	s_movk_i32 s0, 0x4000
	v_cmp_gt_i32_e32 vcc, s0, v1
	s_and_saveexec_b64 s[4:5], vcc
	s_cbranch_execz .LBB0_823
	v_and_b32_e32 v3, 64, v216
	v_add_u32_e32 v3, 64, v3
	v_xor_b32_e32 v5, 32, v216
	v_cmp_lt_i32_e64 s[2:3], v5, v3
	s_waitcnt vmcnt(1)
	v_xor_b32_e32 v6, 16, v216
	s_ashr_i32 s9, s8, 31
	v_cndmask_b32_e64 v5, v216, v5, s[2:3]
	v_cmp_lt_i32_e64 s[2:3], v6, v3
	v_readlane_b32 s0, v252, 34
	v_readlane_b32 s1, v252, 35
	v_cndmask_b32_e64 v6, v216, v6, s[2:3]
	s_waitcnt vmcnt(0)
	v_lshlrev_b32_e32 v10, 2, v6
	v_xor_b32_e32 v6, 8, v216
	v_cmp_lt_i32_e64 s[2:3], v6, v3
	v_and_b32_e32 v15, 63, v158
	s_lshl_b32 s6, s87, 3
	v_cndmask_b32_e64 v6, v216, v6, s[2:3]
	v_lshlrev_b32_e32 v11, 2, v6
	v_xor_b32_e32 v6, 4, v216
	v_cmp_lt_i32_e64 s[2:3], v6, v3
	s_ashr_i32 s7, s6, 31
	v_cmp_eq_u32_e32 vcc, 0, v15
	v_cndmask_b32_e64 v6, v216, v6, s[2:3]
	v_lshlrev_b32_e32 v12, 2, v6
	v_xor_b32_e32 v6, 2, v216
	v_cmp_lt_i32_e64 s[2:3], v6, v3
	v_lshlrev_b32_e32 v5, 2, v5
	s_lshl_b64 s[10:11], s[6:7], 12
	v_cndmask_b32_e64 v6, v216, v6, s[2:3]
	v_lshlrev_b32_e32 v13, 2, v6
	v_xor_b32_e32 v6, 1, v216
	v_cmp_lt_i32_e64 s[2:3], v6, v3
	s_lshl_b64 s[12:13], s[6:7], 11
	s_mov_b64 s[14:15], 0
	v_cndmask_b32_e64 v3, v216, v6, s[2:3]
	v_lshlrev_b32_e32 v14, 2, v3
	v_ashrrev_i32_e32 v3, 31, v2
	v_lshl_add_u64 v[8:9], v[2:3], 0, s[8:9]
	v_lshl_add_u64 v[2:3], v[8:9], 4, s[0:1]
	s_waitcnt lgkmcnt(0)
	v_lshlrev_b64 v[6:7], 12, v[8:9]
	v_readlane_b32 s0, v254, 47
	v_lshl_or_b32 v6, v15, 4, v6
	v_readlane_b32 s1, v254, 48
	v_lshlrev_b64 v[8:9], 11, v[8:9]
	v_lshl_or_b32 v8, v15, 3, v8
	v_lshl_add_u64 v[6:7], s[0:1], 0, v[6:7]
	v_readlane_b32 s0, v253, 57
	v_readlane_b32 s1, v253, 58
	s_lshl_b64 s[8:9], s[6:7], 4
	s_nop 0
	v_lshl_add_u64 v[8:9], s[0:1], 0, v[8:9]
	s_branch .LBB0_821
